# counted post-epilogue vmcnt extended to IN/GLU/WO/DOWN K-loops (flag s99), unit-top drains removed in GLU/DOWN
# baseline (speedup 1.0000x reference)
;     __device__ __forceinline__ bool next(int i, int& pm, int& pn, int& k0, int& nk, int& slice, int& src) const {
;         const long L = (long)i * G + c;
;         pm = 0; pn = 0; k0 = 0; nk = nt; slice = -1; src = 0;
;         if (L < nwg) {
;             int wgid = (int)L; { const int q = nwg / NXCD, r = nwg % NXCD, xcd = wgid % NXCD, off = wgid / NXCD; wgid = (xcd < r ? xcd * (q + 1) : r * (q + 1) + (xcd - r) * q) + off; }
;             const int nig = WGM * nN, gid = wgid / nig, fm = gid * WGM, gsz = (nM - fm) < WGM ? (nM - fm) : WGM;
;             pm = fm + ((wgid % nig) % gsz); pn = (wgid % nig) / gsz; return true;
; template <int EPI> ...
;     ...
;     if (!S.next(0, cur_pm, cur_pn, cur_k0, cur_nk, cur_slice, cur_src)) return;
.LBB0_118:
	s_or_b64 exec, exec, s[0:1]
	v_readlane_b32 s3, v244, 33
	v_mov_b32_e32 v10, v0
	s_cmpk_lt_i32 s3, 0x35a
	s_waitcnt lgkmcnt(0)
	s_barrier
	s_mov_b32 s99, 0
	s_mov_b32 s4, 0
	v_readfirstlane_b32 s12, v10
	s_cselect_b64 s[0:1], -1, 0
	s_cmpk_gt_i32 s3, 0x359
	s_mov_b32 s6, 0
	s_cbranch_scc1 .LBB0_124
	v_readlane_b32 s5, v244, 33
	s_ashr_i32 s3, s5, 31
	s_lshr_b32 s3, s3, 29
	s_add_i32 s3, s5, s3
	s_and_b32 s4, s3, -8
	s_sub_i32 s6, s5, s4
	s_cmp_gt_i32 s6, 1
	s_cbranch_scc0 .LBB0_121
	s_mul_i32 s4, s6, 0x6b
	s_add_i32 s7, s4, 2
	s_cbranch_execz .LBB0_122
	s_branch .LBB0_123

; #define PG8_STAGE(bufoff, gbase) do { _Pragma("unroll") for (int _i = 0; _i < 2; ++_i) \
;         __builtin_amdgcn_global_load_lds((const unsigned*)((const char*)(gbase) + voff[_i]), (LAS unsigned*)(lds + (bufoff) + ldsw + _i * 8192), 16, 0, 0); } while (0)
; #define PG8_LDA(dst, b, h) do { _Pragma("unroll") for (int m = 0; m < 4; ++m) _Pragma("unroll") for (int k = 0; k < 2; ++k) dst[m][k] = *(const LAS bf16x8*)(lds + PG8_SA(b, h) + aoff + m * 2048 + k * 1024); } while (0)
; #define PG8_LDB(dst, b, h) do { _Pragma("unroll") for (int n = 0; n < 2; ++n) _Pragma("unroll") for (int k = 0; k < 2; ++k) dst[n][k] = *(const LAS bf16x8*)(lds + PG8_SB(b, h) + boff + n * 2048 + k * 1024); } while (0)
; #define PG8_MMA(ai, bj, At, Bt) do { __builtin_amdgcn_s_setprio(1); _Pragma("unroll") for (int m = 0; m < 4; ++m) _Pragma("unroll") for (int n = 0; n < 2; ++n) _Pragma("unroll") for (int k = 0; k < 2; ++k) \
;         acc[ai][bj][m][n] = __builtin_amdgcn_mfma_f32_16x16x32_bf16(Bt[n][k], At[m][k], acc[ai][bj][m][n], 0, 0, 0); __builtin_amdgcn_s_setprio(0); } while (0)
; #define PG8_WAIT_V(n) asm volatile("s_waitcnt vmcnt(" #n ")" ::: "memory")
; #define PG8_WAIT_L(n) asm volatile("s_waitcnt lgkmcnt(" #n ")" ::: "memory")
; #define PG8_BAR __builtin_amdgcn_s_barrier()
; #define PG8_SCHED __builtin_amdgcn_sched_barrier(0)
; template <int EPI> ...
;     ...
;         for (int t = 0; t < cnk; t += 2) {
;             const bool last = (t == cnk - 2);
;             const char* a1 = cA + (size_t)(t + 1) * kstep;
;             const char* a2 = last ? nA : cA + (size_t)(t + 2) * kstep; const char* b2 = last ? nB : cB + (size_t)(t + 2) * kstep;
;             const char* a3 = a2 + kstep; const char* b3 = b2 + kstep;
;             PG8_LDB(B0, 0, 0); PG8_LDB(B1, 0, 1); PG8_SCHED; PG8_LDA(At, 0, 0); PG8_STAGE(PG8_SA(1, 1), a1 + hstep);
;             PG8_WAIT_V(8); PG8_WAIT_L(0); PG8_BAR; PG8_MMA(0, 0, At, B0); PG8_MMA(0, 1, At, B1); PG8_BAR; PG8_SCHED;
.LBB0_137:
	ds_read_b128 v[130:133], v178
	ds_read_b128 v[164:167], v178 offset:1024
	ds_read_b128 v[168:171], v178 offset:2048
	ds_read_b128 v[172:175], v178 offset:3072
	ds_read_b128 v[188:191], v179
	ds_read_b128 v[192:195], v179 offset:1024
	ds_read_b128 v[196:199], v179 offset:2048
	ds_read_b128 v[200:203], v179 offset:3072
	s_add_u32 s28, s26, 0xfffc0080
	s_addc_u32 s29, s27, -1
	s_cmp_eq_u32 s36, 12
	s_cselect_b32 s31, s5, s29
	s_cselect_b32 s30, s7, s28
	s_cselect_b32 s29, s19, s35
	s_cselect_b32 s28, s21, s34
	v_lshl_add_u64 v[176:177], s[26:27], 0, v[156:157]
	s_add_i32 m0, s42, 0xc000
	ds_read_b128 v[204:207], v180
	ds_read_b128 v[208:211], v180 offset:1024
	ds_read_b128 v[212:215], v180 offset:2048
	ds_read_b128 v[216:219], v180 offset:3072
	ds_read_b128 v[220:223], v180 offset:4096
	ds_read_b128 v[224:227], v180 offset:5120
	ds_read_b128 v[228:231], v180 offset:6144
	ds_read_b128 v[232:235], v180 offset:7168
	global_load_lds_dwordx4 v[176:177], off
	v_lshl_add_u64 v[176:177], s[26:27], 0, v[158:159]
	s_add_i32 m0, s42, 0xe000
	s_nop 0
	global_load_lds_dwordx4 v[176:177], off
	s_cmp_eq_u32 s99, 0
	s_cbranch_scc1 .Lrx_IN_s0
	s_waitcnt vmcnt(24)
	s_branch .Lrx_IN_d0

; #define PG8_STAGE(bufoff, gbase) do { _Pragma("unroll") for (int _i = 0; _i < 2; ++_i) \
;         __builtin_amdgcn_global_load_lds((const unsigned*)((const char*)(gbase) + voff[_i]), (LAS unsigned*)(lds + (bufoff) + ldsw + _i * 8192), 16, 0, 0); } while (0)
; #define PG8_LDA(dst, b, h) do { _Pragma("unroll") for (int m = 0; m < 4; ++m) _Pragma("unroll") for (int k = 0; k < 2; ++k) dst[m][k] = *(const LAS bf16x8*)(lds + PG8_SA(b, h) + aoff + m * 2048 + k * 1024); } while (0)
; #define PG8_MMA(ai, bj, At, Bt) do { __builtin_amdgcn_s_setprio(1); _Pragma("unroll") for (int m = 0; m < 4; ++m) _Pragma("unroll") for (int n = 0; n < 2; ++n) _Pragma("unroll") for (int k = 0; k < 2; ++k) \
;         acc[ai][bj][m][n] = __builtin_amdgcn_mfma_f32_16x16x32_bf16(Bt[n][k], At[m][k], acc[ai][bj][m][n], 0, 0, 0); __builtin_amdgcn_s_setprio(0); } while (0)
; #define PG8_WAIT_V(n) asm volatile("s_waitcnt vmcnt(" #n ")" ::: "memory")
; #define PG8_WAIT_L(n) asm volatile("s_waitcnt lgkmcnt(" #n ")" ::: "memory")
; #define PG8_BAR __builtin_amdgcn_s_barrier()
; #define PG8_SCHED __builtin_amdgcn_sched_barrier(0)
; template <int EPI> ...
;     ...
;             PG8_WAIT_V(8); PG8_WAIT_L(0); PG8_BAR; PG8_MMA(0, 0, At, B0); PG8_MMA(0, 1, At, B1); PG8_BAR; PG8_SCHED;
;             PG8_LDA(At, 0, 1); PG8_STAGE(PG8_SB(0, 0), b2); PG8_STAGE(PG8_SB(0, 1), b2 + hstep); PG8_STAGE(PG8_SA(0, 0), a2);
.Lrx_IN_d0:
	s_waitcnt lgkmcnt(0)
	s_barrier
	s_setprio 1
	s_waitcnt lgkmcnt(0)
	v_mfma_f32_16x16x32_bf16 v[126:129], v[130:133], v[204:207], v[126:129]
	v_mfma_f32_16x16x32_bf16 v[122:125], v[168:171], v[204:207], v[122:125]
	v_mfma_f32_16x16x32_bf16 v[118:121], v[130:133], v[212:215], v[118:121]
	v_mfma_f32_16x16x32_bf16 v[114:117], v[168:171], v[212:215], v[114:117]
	v_mfma_f32_16x16x32_bf16 v[110:113], v[130:133], v[220:223], v[110:113]
	v_mfma_f32_16x16x32_bf16 v[106:109], v[168:171], v[220:223], v[106:109]
	v_mfma_f32_16x16x32_bf16 v[102:105], v[130:133], v[228:231], v[102:105]
	v_mfma_f32_16x16x32_bf16 v[98:101], v[168:171], v[228:231], v[98:101]
	v_mfma_f32_16x16x32_bf16 v[126:129], v[164:167], v[208:211], v[126:129]
	v_mfma_f32_16x16x32_bf16 v[122:125], v[172:175], v[208:211], v[122:125]
	v_mfma_f32_16x16x32_bf16 v[118:121], v[164:167], v[216:219], v[118:121]
	v_mfma_f32_16x16x32_bf16 v[114:117], v[172:175], v[216:219], v[114:117]
	v_mfma_f32_16x16x32_bf16 v[110:113], v[164:167], v[224:227], v[110:113]
	v_mfma_f32_16x16x32_bf16 v[106:109], v[172:175], v[224:227], v[106:109]
	v_mfma_f32_16x16x32_bf16 v[102:105], v[164:167], v[232:235], v[102:105]
	v_mfma_f32_16x16x32_bf16 v[98:101], v[172:175], v[232:235], v[98:101]
	s_setprio 0
	s_setprio 1
	v_mfma_f32_16x16x32_bf16 v[62:65], v[188:191], v[204:207], v[62:65]
	v_mfma_f32_16x16x32_bf16 v[58:61], v[196:199], v[204:207], v[58:61]
	v_mfma_f32_16x16x32_bf16 v[54:57], v[188:191], v[212:215], v[54:57]
	v_mfma_f32_16x16x32_bf16 v[50:53], v[196:199], v[212:215], v[50:53]
	v_mfma_f32_16x16x32_bf16 v[46:49], v[188:191], v[220:223], v[46:49]
	v_mfma_f32_16x16x32_bf16 v[42:45], v[196:199], v[220:223], v[42:45]
	v_mfma_f32_16x16x32_bf16 v[38:41], v[188:191], v[228:231], v[38:41]
	v_mfma_f32_16x16x32_bf16 v[34:37], v[196:199], v[228:231], v[34:37]
	v_mfma_f32_16x16x32_bf16 v[62:65], v[192:195], v[208:211], v[62:65]
	v_mfma_f32_16x16x32_bf16 v[58:61], v[200:203], v[208:211], v[58:61]
	v_mfma_f32_16x16x32_bf16 v[54:57], v[192:195], v[216:219], v[54:57]
	v_mfma_f32_16x16x32_bf16 v[50:53], v[200:203], v[216:219], v[50:53]
	v_mfma_f32_16x16x32_bf16 v[46:49], v[192:195], v[224:227], v[46:49]
	v_mfma_f32_16x16x32_bf16 v[42:45], v[200:203], v[224:227], v[42:45]
	v_mfma_f32_16x16x32_bf16 v[38:41], v[192:195], v[232:235], v[38:41]
	v_mfma_f32_16x16x32_bf16 v[34:37], v[200:203], v[232:235], v[34:37]
	s_setprio 0
	s_barrier
	s_add_i32 s37, s55, s41
	v_lshl_add_u64 v[176:177], s[28:29], 0, v[136:137]
	s_mov_b32 m0, s37
	ds_read_b128 v[204:207], v180 offset:16384
	ds_read_b128 v[208:211], v180 offset:17408
	ds_read_b128 v[212:215], v180 offset:18432
	ds_read_b128 v[216:219], v180 offset:19456
	ds_read_b128 v[220:223], v180 offset:20480
	ds_read_b128 v[224:227], v180 offset:21504
	ds_read_b128 v[228:231], v180 offset:22528
	ds_read_b128 v[232:235], v180 offset:23552
	global_load_lds_dwordx4 v[176:177], off
	s_add_i32 m0, s37, 0x2000
	s_add_u32 s38, s28, 0x40000
	v_lshl_add_u64 v[236:237], s[28:29], 0, v[138:139]
	s_addc_u32 s39, s29, 0
	s_add_i32 s37, s56, s41
	global_load_lds_dwordx4 v[236:237], off
	v_lshl_add_u64 v[238:239], s[38:39], 0, v[136:137]
	s_mov_b32 m0, s37
	v_lshl_add_u64 v[240:241], s[30:31], 0, v[138:139]
	global_load_lds_dwordx4 v[238:239], off
	v_lshl_add_u64 v[238:239], s[38:39], 0, v[138:139]
	s_add_i32 m0, s37, 0x2000
	s_nop 0
	global_load_lds_dwordx4 v[238:239], off
	v_lshl_add_u64 v[238:239], s[30:31], 0, v[136:137]
	s_mov_b32 m0, s42
	s_nop 0
	global_load_lds_dwordx4 v[238:239], off
	s_mov_b32 m0, s43
	s_nop 0
	global_load_lds_dwordx4 v[240:241], off
	s_cmp_eq_u32 s99, 0
	s_cbranch_scc1 .Lrx_IN_s1
	s_waitcnt vmcnt(24)
	s_branch .Lrx_IN_d1

; #define PG8_STAGE(bufoff, gbase) do { _Pragma("unroll") for (int _i = 0; _i < 2; ++_i) \
;         __builtin_amdgcn_global_load_lds((const unsigned*)((const char*)(gbase) + voff[_i]), (LAS unsigned*)(lds + (bufoff) + ldsw + _i * 8192), 16, 0, 0); } while (0)
; #define PG8_LDA(dst, b, h) do { _Pragma("unroll") for (int m = 0; m < 4; ++m) _Pragma("unroll") for (int k = 0; k < 2; ++k) dst[m][k] = *(const LAS bf16x8*)(lds + PG8_SA(b, h) + aoff + m * 2048 + k * 1024); } while (0)
; #define PG8_LDB(dst, b, h) do { _Pragma("unroll") for (int n = 0; n < 2; ++n) _Pragma("unroll") for (int k = 0; k < 2; ++k) dst[n][k] = *(const LAS bf16x8*)(lds + PG8_SB(b, h) + boff + n * 2048 + k * 1024); } while (0)
; #define PG8_MMA(ai, bj, At, Bt) do { __builtin_amdgcn_s_setprio(1); _Pragma("unroll") for (int m = 0; m < 4; ++m) _Pragma("unroll") for (int n = 0; n < 2; ++n) _Pragma("unroll") for (int k = 0; k < 2; ++k) \
;         acc[ai][bj][m][n] = __builtin_amdgcn_mfma_f32_16x16x32_bf16(Bt[n][k], At[m][k], acc[ai][bj][m][n], 0, 0, 0); __builtin_amdgcn_s_setprio(0); } while (0)
; #define PG8_WAIT_V(n) asm volatile("s_waitcnt vmcnt(" #n ")" ::: "memory")
; #define PG8_WAIT_L(n) asm volatile("s_waitcnt lgkmcnt(" #n ")" ::: "memory")
; #define PG8_BAR __builtin_amdgcn_s_barrier()
; #define PG8_SCHED __builtin_amdgcn_sched_barrier(0)
; template <int EPI> ...
;     ...
;             PG8_LDA(At, 0, 1); PG8_STAGE(PG8_SB(0, 0), b2); PG8_STAGE(PG8_SB(0, 1), b2 + hstep); PG8_STAGE(PG8_SA(0, 0), a2);
;             PG8_WAIT_V(8); PG8_WAIT_L(0); PG8_BAR; PG8_MMA(1, 0, At, B0); PG8_MMA(1, 1, At, B1); PG8_BAR; PG8_SCHED;
;             PG8_LDB(B0, 1, 0); PG8_LDB(B1, 1, 1); PG8_SCHED; PG8_LDA(At, 1, 0); PG8_STAGE(PG8_SA(0, 1), a2 + hstep);
;             PG8_WAIT_V(8); PG8_WAIT_L(0); PG8_BAR; PG8_MMA(0, 0, At, B0); PG8_MMA(0, 1, At, B1); PG8_BAR; PG8_SCHED;
.Lrx_IN_d1:
	s_mov_b32 s99, 0
	s_waitcnt lgkmcnt(0)
	s_barrier
	s_setprio 1
	s_waitcnt lgkmcnt(0)
	v_mfma_f32_16x16x32_bf16 v[94:97], v[130:133], v[204:207], v[94:97]
	v_mfma_f32_16x16x32_bf16 v[90:93], v[168:171], v[204:207], v[90:93]
	v_mfma_f32_16x16x32_bf16 v[86:89], v[130:133], v[212:215], v[86:89]
	v_mfma_f32_16x16x32_bf16 v[82:85], v[168:171], v[212:215], v[82:85]
	v_mfma_f32_16x16x32_bf16 v[78:81], v[130:133], v[220:223], v[78:81]
	v_mfma_f32_16x16x32_bf16 v[74:77], v[168:171], v[220:223], v[74:77]
	v_mfma_f32_16x16x32_bf16 v[70:73], v[130:133], v[228:231], v[70:73]
	v_mfma_f32_16x16x32_bf16 v[66:69], v[168:171], v[228:231], v[66:69]
	v_mfma_f32_16x16x32_bf16 v[94:97], v[164:167], v[208:211], v[94:97]
	v_mfma_f32_16x16x32_bf16 v[90:93], v[172:175], v[208:211], v[90:93]
	v_mfma_f32_16x16x32_bf16 v[86:89], v[164:167], v[216:219], v[86:89]
	v_mfma_f32_16x16x32_bf16 v[82:85], v[172:175], v[216:219], v[82:85]
	v_mfma_f32_16x16x32_bf16 v[78:81], v[164:167], v[224:227], v[78:81]
	v_mfma_f32_16x16x32_bf16 v[74:77], v[172:175], v[224:227], v[74:77]
	v_mfma_f32_16x16x32_bf16 v[70:73], v[164:167], v[232:235], v[70:73]
	v_mfma_f32_16x16x32_bf16 v[66:69], v[172:175], v[232:235], v[66:69]
	s_setprio 0
	s_setprio 1
	v_mfma_f32_16x16x32_bf16 v[30:33], v[188:191], v[204:207], v[30:33]
	v_mfma_f32_16x16x32_bf16 v[26:29], v[196:199], v[204:207], v[26:29]
	v_mfma_f32_16x16x32_bf16 v[22:25], v[188:191], v[212:215], v[22:25]
	v_mfma_f32_16x16x32_bf16 v[18:21], v[196:199], v[212:215], v[18:21]
	v_mfma_f32_16x16x32_bf16 v[14:17], v[188:191], v[220:223], v[14:17]
	v_mfma_f32_16x16x32_bf16 v[10:13], v[196:199], v[220:223], v[10:13]
	v_mfma_f32_16x16x32_bf16 v[6:9], v[188:191], v[228:231], v[6:9]
	v_mfma_f32_16x16x32_bf16 v[2:5], v[196:199], v[228:231], v[2:5]
	v_mfma_f32_16x16x32_bf16 v[30:33], v[192:195], v[208:211], v[30:33]
	v_mfma_f32_16x16x32_bf16 v[26:29], v[200:203], v[208:211], v[26:29]
	v_mfma_f32_16x16x32_bf16 v[22:25], v[192:195], v[216:219], v[22:25]
	v_mfma_f32_16x16x32_bf16 v[18:21], v[200:203], v[216:219], v[18:21]
	v_mfma_f32_16x16x32_bf16 v[14:17], v[192:195], v[224:227], v[14:17]
	v_mfma_f32_16x16x32_bf16 v[10:13], v[200:203], v[224:227], v[10:13]
	v_mfma_f32_16x16x32_bf16 v[6:9], v[192:195], v[232:235], v[6:9]
	v_mfma_f32_16x16x32_bf16 v[2:5], v[200:203], v[232:235], v[2:5]
	s_setprio 0
	s_barrier
	s_add_i32 s37, 0, 0x18000
	v_add_u32_e32 v140, s37, v147
	s_add_i32 s38, 0, 0x1c000
	ds_read_b128 v[130:133], v140
	ds_read_b128 v[164:167], v140 offset:1024
	ds_read_b128 v[168:171], v140 offset:2048
	ds_read_b128 v[172:175], v140 offset:3072
	v_add_u32_e32 v140, s38, v147
	ds_read_b128 v[188:191], v140
	ds_read_b128 v[192:195], v140 offset:1024
	ds_read_b128 v[196:199], v140 offset:2048
	ds_read_b128 v[200:203], v140 offset:3072
	s_add_u32 s30, s30, 0x40000
	s_addc_u32 s31, s31, 0
	s_mov_b32 m0, s44
	v_lshl_add_u64 v[242:243], s[30:31], 0, v[136:137]
	ds_read_b128 v[204:207], v180 offset:32768
	ds_read_b128 v[208:211], v180 offset:33792
	ds_read_b128 v[212:215], v180 offset:34816
	ds_read_b128 v[216:219], v180 offset:35840
	ds_read_b128 v[220:223], v180 offset:36864
	ds_read_b128 v[224:227], v180 offset:37888
	ds_read_b128 v[228:231], v180 offset:38912
	ds_read_b128 v[232:235], v180 offset:39936
	global_load_lds_dwordx4 v[242:243], off
	v_lshl_add_u64 v[242:243], s[30:31], 0, v[138:139]
	s_mov_b32 m0, s45
	s_nop 0
	global_load_lds_dwordx4 v[242:243], off
	s_waitcnt vmcnt(8)
	s_waitcnt lgkmcnt(0)
	s_barrier
	s_setprio 1
	s_waitcnt lgkmcnt(0)
	v_mfma_f32_16x16x32_bf16 v[126:129], v[130:133], v[204:207], v[126:129]
	v_mfma_f32_16x16x32_bf16 v[122:125], v[168:171], v[204:207], v[122:125]
	v_mfma_f32_16x16x32_bf16 v[118:121], v[130:133], v[212:215], v[118:121]
	v_mfma_f32_16x16x32_bf16 v[114:117], v[168:171], v[212:215], v[114:117]
	v_mfma_f32_16x16x32_bf16 v[110:113], v[130:133], v[220:223], v[110:113]
	v_mfma_f32_16x16x32_bf16 v[106:109], v[168:171], v[220:223], v[106:109]
	v_mfma_f32_16x16x32_bf16 v[102:105], v[130:133], v[228:231], v[102:105]
	v_mfma_f32_16x16x32_bf16 v[98:101], v[168:171], v[228:231], v[98:101]
	v_mfma_f32_16x16x32_bf16 v[126:129], v[164:167], v[208:211], v[126:129]
	v_mfma_f32_16x16x32_bf16 v[122:125], v[172:175], v[208:211], v[122:125]
	v_mfma_f32_16x16x32_bf16 v[118:121], v[164:167], v[216:219], v[118:121]
	v_mfma_f32_16x16x32_bf16 v[114:117], v[172:175], v[216:219], v[114:117]
	v_mfma_f32_16x16x32_bf16 v[110:113], v[164:167], v[224:227], v[110:113]
	v_mfma_f32_16x16x32_bf16 v[106:109], v[172:175], v[224:227], v[106:109]
	v_mfma_f32_16x16x32_bf16 v[102:105], v[164:167], v[232:235], v[102:105]
	v_mfma_f32_16x16x32_bf16 v[98:101], v[172:175], v[232:235], v[98:101]
	s_setprio 0
	s_setprio 1
	v_mfma_f32_16x16x32_bf16 v[62:65], v[188:191], v[204:207], v[62:65]
	v_mfma_f32_16x16x32_bf16 v[58:61], v[196:199], v[204:207], v[58:61]
	v_mfma_f32_16x16x32_bf16 v[54:57], v[188:191], v[212:215], v[54:57]
	v_mfma_f32_16x16x32_bf16 v[50:53], v[196:199], v[212:215], v[50:53]
	v_mfma_f32_16x16x32_bf16 v[46:49], v[188:191], v[220:223], v[46:49]
	v_mfma_f32_16x16x32_bf16 v[42:45], v[196:199], v[220:223], v[42:45]
	v_mfma_f32_16x16x32_bf16 v[38:41], v[188:191], v[228:231], v[38:41]
	v_mfma_f32_16x16x32_bf16 v[34:37], v[196:199], v[228:231], v[34:37]
	v_mfma_f32_16x16x32_bf16 v[62:65], v[192:195], v[208:211], v[62:65]
	v_mfma_f32_16x16x32_bf16 v[58:61], v[200:203], v[208:211], v[58:61]
	v_mfma_f32_16x16x32_bf16 v[54:57], v[192:195], v[216:219], v[54:57]
	v_mfma_f32_16x16x32_bf16 v[50:53], v[200:203], v[216:219], v[50:53]
	v_mfma_f32_16x16x32_bf16 v[46:49], v[192:195], v[224:227], v[46:49]
	v_mfma_f32_16x16x32_bf16 v[42:45], v[200:203], v[224:227], v[42:45]
	v_mfma_f32_16x16x32_bf16 v[38:41], v[192:195], v[232:235], v[38:41]
	v_mfma_f32_16x16x32_bf16 v[34:37], v[200:203], v[232:235], v[34:37]
	s_setprio 0
	s_barrier
; #define PG8_STAGE(bufoff, gbase) do { _Pragma("unroll") for (int _i = 0; _i < 2; ++_i) \
;         __builtin_amdgcn_global_load_lds((const unsigned*)((const char*)(gbase) + voff[_i]), (LAS unsigned*)(lds + (bufoff) + ldsw + _i * 8192), 16, 0, 0); } while (0)
; #define PG8_LDA(dst, b, h) do { _Pragma("unroll") for (int m = 0; m < 4; ++m) _Pragma("unroll") for (int k = 0; k < 2; ++k) dst[m][k] = *(const LAS bf16x8*)(lds + PG8_SA(b, h) + aoff + m * 2048 + k * 1024); } while (0)
; #define PG8_MMA(ai, bj, At, Bt) do { __builtin_amdgcn_s_setprio(1); _Pragma("unroll") for (int m = 0; m < 4; ++m) _Pragma("unroll") for (int n = 0; n < 2; ++n) _Pragma("unroll") for (int k = 0; k < 2; ++k) \
;         acc[ai][bj][m][n] = __builtin_amdgcn_mfma_f32_16x16x32_bf16(Bt[n][k], At[m][k], acc[ai][bj][m][n], 0, 0, 0); __builtin_amdgcn_s_setprio(0); } while (0)
; #define PG8_WAIT_V(n) asm volatile("s_waitcnt vmcnt(" #n ")" ::: "memory")
; #define PG8_WAIT_L(n) asm volatile("s_waitcnt lgkmcnt(" #n ")" ::: "memory")
; #define PG8_BAR __builtin_amdgcn_s_barrier()
; #define PG8_SCHED __builtin_amdgcn_sched_barrier(0)
; template <int EPI> ...
;     ...
;             PG8_LDA(At, 1, 1); PG8_STAGE(PG8_SB(1, 0), b3); PG8_STAGE(PG8_SB(1, 1), b3 + hstep); PG8_STAGE(PG8_SA(1, 0), a3);
;             PG8_WAIT_V(8); PG8_WAIT_L(0); PG8_BAR; PG8_MMA(1, 0, At, B0); PG8_MMA(1, 1, At, B1); PG8_BAR; PG8_SCHED;
;         }
;         if (wr == 0) PG8_BAR;
	s_add_i32 s30, s37, s41
	v_lshl_add_u64 v[176:177], v[176:177], 0, s[10:11]
	s_mov_b32 m0, s30
	ds_read_b128 v[204:207], v180 offset:49152
	ds_read_b128 v[208:211], v180 offset:50176
	ds_read_b128 v[212:215], v180 offset:51200
	ds_read_b128 v[216:219], v180 offset:52224
	ds_read_b128 v[220:223], v180 offset:53248
	ds_read_b128 v[224:227], v180 offset:54272
	ds_read_b128 v[228:231], v180 offset:55296
	ds_read_b128 v[232:235], v180 offset:56320
	global_load_lds_dwordx4 v[176:177], off
	s_add_i32 m0, s30, 0x2000
	s_add_u32 s28, s28, 0x40080
	v_lshl_add_u64 v[176:177], v[236:237], 0, s[10:11]
	s_addc_u32 s29, s29, 0
	s_add_i32 s30, s38, s41
	global_load_lds_dwordx4 v[176:177], off
	v_lshl_add_u64 v[176:177], s[28:29], 0, v[136:137]
	s_mov_b32 m0, s30
	s_nop 0
	global_load_lds_dwordx4 v[176:177], off
	v_lshl_add_u64 v[176:177], s[28:29], 0, v[138:139]
	s_add_i32 m0, s30, 0x2000
	s_nop 0
	global_load_lds_dwordx4 v[176:177], off
	v_lshl_add_u64 v[176:177], v[238:239], 0, s[10:11]
	s_mov_b32 m0, s48
	s_nop 0
	global_load_lds_dwordx4 v[176:177], off
	v_lshl_add_u64 v[176:177], v[240:241], 0, s[10:11]
	s_mov_b32 m0, s49
	s_nop 0
	global_load_lds_dwordx4 v[176:177], off
	s_waitcnt vmcnt(8)
	s_waitcnt lgkmcnt(0)
	s_barrier
	s_setprio 1
	s_waitcnt lgkmcnt(0)
	v_mfma_f32_16x16x32_bf16 v[94:97], v[130:133], v[204:207], v[94:97]
	v_mfma_f32_16x16x32_bf16 v[90:93], v[168:171], v[204:207], v[90:93]
	v_mfma_f32_16x16x32_bf16 v[86:89], v[130:133], v[212:215], v[86:89]
	v_mfma_f32_16x16x32_bf16 v[82:85], v[168:171], v[212:215], v[82:85]
	v_mfma_f32_16x16x32_bf16 v[78:81], v[130:133], v[220:223], v[78:81]
	v_mfma_f32_16x16x32_bf16 v[74:77], v[168:171], v[220:223], v[74:77]
	v_mfma_f32_16x16x32_bf16 v[70:73], v[130:133], v[228:231], v[70:73]
	v_mfma_f32_16x16x32_bf16 v[66:69], v[168:171], v[228:231], v[66:69]
	v_mfma_f32_16x16x32_bf16 v[94:97], v[164:167], v[208:211], v[94:97]
	v_mfma_f32_16x16x32_bf16 v[90:93], v[172:175], v[208:211], v[90:93]
	v_mfma_f32_16x16x32_bf16 v[86:89], v[164:167], v[216:219], v[86:89]
	v_mfma_f32_16x16x32_bf16 v[82:85], v[172:175], v[216:219], v[82:85]
	v_mfma_f32_16x16x32_bf16 v[78:81], v[164:167], v[224:227], v[78:81]
	v_mfma_f32_16x16x32_bf16 v[74:77], v[172:175], v[224:227], v[74:77]
	v_mfma_f32_16x16x32_bf16 v[70:73], v[164:167], v[232:235], v[70:73]
	v_mfma_f32_16x16x32_bf16 v[66:69], v[172:175], v[232:235], v[66:69]
	s_setprio 0
	s_setprio 1
	v_mfma_f32_16x16x32_bf16 v[30:33], v[188:191], v[204:207], v[30:33]
	v_mfma_f32_16x16x32_bf16 v[26:29], v[196:199], v[204:207], v[26:29]
	v_mfma_f32_16x16x32_bf16 v[22:25], v[188:191], v[212:215], v[22:25]
	v_mfma_f32_16x16x32_bf16 v[18:21], v[196:199], v[212:215], v[18:21]
	v_mfma_f32_16x16x32_bf16 v[14:17], v[188:191], v[220:223], v[14:17]
	v_mfma_f32_16x16x32_bf16 v[10:13], v[196:199], v[220:223], v[10:13]
	v_mfma_f32_16x16x32_bf16 v[6:9], v[188:191], v[228:231], v[6:9]
	v_mfma_f32_16x16x32_bf16 v[2:5], v[196:199], v[228:231], v[2:5]
	v_mfma_f32_16x16x32_bf16 v[30:33], v[192:195], v[208:211], v[30:33]
	v_mfma_f32_16x16x32_bf16 v[26:29], v[200:203], v[208:211], v[26:29]
	v_mfma_f32_16x16x32_bf16 v[22:25], v[192:195], v[216:219], v[22:25]
	v_mfma_f32_16x16x32_bf16 v[18:21], v[200:203], v[216:219], v[18:21]
	v_mfma_f32_16x16x32_bf16 v[14:17], v[192:195], v[224:227], v[14:17]
	v_mfma_f32_16x16x32_bf16 v[10:13], v[200:203], v[224:227], v[10:13]
	v_mfma_f32_16x16x32_bf16 v[6:9], v[192:195], v[232:235], v[6:9]
	v_mfma_f32_16x16x32_bf16 v[2:5], v[200:203], v[232:235], v[2:5]
	s_setprio 0
	s_barrier
	s_add_i32 s36, s36, 2
	s_add_u32 s26, s26, 0x100
	s_addc_u32 s27, s27, 0
	s_add_u32 s34, s34, 0x100
	s_addc_u32 s35, s35, 0
	s_cmp_gt_u32 s36, 13
	s_cbranch_scc0 .LBB0_137
	s_mov_b32 s99, 1
	s_and_b64 vcc, exec, s[12:13]
	s_cbranch_vccz .LBB0_140
	s_barrier

;     __device__ __forceinline__ bool next(int i, int& pm, int& pn, int& k0, int& nk, int& slice, int& src) const {
;     ...
;         if (nsplit == 0) return false;
;         int sidx = (int)(L - nwg);
;         if (sidx >= nslice_items) return false;
;         int ncol = nN;
;         if (glu && sidx >= 64) { sidx -= 64; src = 1; ncol = 4; }
;         const int tl = sidx / nsplit; slice = sidx - tl * nsplit; pm = 64 + tl / ncol; pn = tl % ncol; nk = nt / nsplit; k0 = slice * nk; return true;
.LBB0_630:
	s_or_b64 exec, exec, s[0:1]
	v_readlane_b32 s4, v244, 0
	v_readlane_b32 s6, v244, 2
	v_readlane_b32 s7, v244, 3
	s_add_u32 s34, s6, 0x7380000
	s_addc_u32 s35, s7, 0
	s_add_u32 s36, s6, 0xce80000
	s_addc_u32 s37, s7, 0
	v_mov_b32_e32 v10, v0
	v_readlane_b32 s7, v244, 33
	s_waitcnt lgkmcnt(0)
	s_barrier
	s_mov_b32 s99, 0
	s_cmpk_gt_i32 s7, 0x1ff
	v_readfirstlane_b32 s14, v10
	v_readlane_b32 s5, v244, 1
	s_cbranch_scc0 .LBB0_633
	s_cmpk_lt_u32 s7, 0x260
	s_mov_b64 s[12:13], 0
	s_cbranch_scc0 .LBB0_634
	s_cmpk_gt_u32 s7, 0x23f
	s_cselect_b64 s[0:1], -1, 0
	v_cndmask_b32_e64 v2, 0, 1, s[0:1]
	s_movk_i32 s4, 0xfdc0
	s_and_b64 s[0:1], s[0:1], exec
	s_cselect_b32 s0, s4, 0xfffffe00
	s_cselect_b32 s1, 2, 3
	s_cselect_b32 s5, 3, 7
	s_add_i32 s4, s0, s7
	s_lshr_b32 s6, s4, 2
	s_bfe_u32 s4, s4, 0x80002
	s_lshr_b32 s1, s4, s1
	s_and_b32 s0, s7, 3
	s_or_b32 s1, s1, 64
	v_readfirstlane_b32 s41, v2
	s_and_b32 s4, s1, 0x7f
	s_and_b32 s6, s6, s5
	s_lshl_b32 s8, s0, 8
	s_mov_b32 s9, 0
	s_mov_b64 s[10:11], -1
	s_mov_b32 s57, 2
	s_and_b64 vcc, exec, s[12:13]
	s_cbranch_vccnz .LBB0_635
	s_branch .LBB0_640

; #define PG8_STAGE(bufoff, gbase) do { _Pragma("unroll") for (int _i = 0; _i < 2; ++_i) \
;         __builtin_amdgcn_global_load_lds((const unsigned*)((const char*)(gbase) + voff[_i]), (LAS unsigned*)(lds + (bufoff) + ldsw + _i * 8192), 16, 0, 0); } while (0)
; #define PG8_LDA(dst, b, h) do { _Pragma("unroll") for (int m = 0; m < 4; ++m) _Pragma("unroll") for (int k = 0; k < 2; ++k) dst[m][k] = *(const LAS bf16x8*)(lds + PG8_SA(b, h) + aoff + m * 2048 + k * 1024); } while (0)
; #define PG8_LDB(dst, b, h) do { _Pragma("unroll") for (int n = 0; n < 2; ++n) _Pragma("unroll") for (int k = 0; k < 2; ++k) dst[n][k] = *(const LAS bf16x8*)(lds + PG8_SB(b, h) + boff + n * 2048 + k * 1024); } while (0)
; #define PG8_WAIT_V(n) asm volatile("s_waitcnt vmcnt(" #n ")" ::: "memory")
; #define PG8_WAIT_L(n) asm volatile("s_waitcnt lgkmcnt(" #n ")" ::: "memory")
; #define PG8_BAR __builtin_amdgcn_s_barrier()
; #define PG8_SCHED __builtin_amdgcn_sched_barrier(0)
; template <int EPI> ...
;     ...
;         const char* nA = has_next ? (const char*)((EPI == EPI_GLU && nxt_src) ? gA2 : gA) + (size_t)nxt_pm * tstep + (size_t)nxt_k0 * kstep : cA;
;         const char* nB = has_next ? (const char*)((EPI == EPI_GLU && nxt_src) ? gBt2 : gBt) + (size_t)nxt_pn * tstep + (size_t)nxt_k0 * kstep : cB;
;         const int cnk = cur_nk;
;         for (int t = 0; t < cnk; t += 2) {
;             const bool last = (t == cnk - 2);
;             const char* a1 = cA + (size_t)(t + 1) * kstep;
;             const char* a2 = last ? nA : cA + (size_t)(t + 2) * kstep; const char* b2 = last ? nB : cB + (size_t)(t + 2) * kstep;
;             const char* a3 = a2 + kstep; const char* b3 = b2 + kstep;
;             PG8_LDB(B0, 0, 0); PG8_LDB(B1, 0, 1); PG8_SCHED; PG8_LDA(At, 0, 0); PG8_STAGE(PG8_SA(1, 1), a1 + hstep);
;             PG8_WAIT_V(8); PG8_WAIT_L(0); PG8_BAR; PG8_MMA(0, 0, At, B0); PG8_MMA(0, 1, At, B1); PG8_BAR; PG8_SCHED;
;     ...
;         for (int a = 0; a < 2; ++a)
; #pragma unroll
;             for (int b = 0; b < 2; ++b)
; #pragma unroll
;                 for (int m = 0; m < 4; ++m)
; #pragma unroll
;                     for (int n = 0; n < 2; ++n) acc[a][b][m][n] = (f32x4){0.f, 0.f, 0.f, 0.f};
;         cur_pm = nxt_pm; cur_pn = nxt_pn; cur_k0 = nxt_k0; cur_nk = nxt_nk; cur_slice = nxt_slice; cur_src = nxt_src; cA = nA; cB = nB; ++ui;
.LBB0_655:
	s_ashr_i32 s19, s18, 31
	s_lshl_b64 s[22:23], s[18:19], 18
	s_cmp_eq_u32 s54, 0
	s_cselect_b32 s17, s96, s34
	s_cselect_b32 s5, s97, s35
	s_cselect_b32 s58, s39, s37
	s_cselect_b32 s59, s38, s36
	s_add_u32 s17, s17, s22
	s_addc_u32 s5, s5, s23
	s_add_u32 s22, s17, s30
	s_addc_u32 s23, s5, s31
	s_and_b64 s[24:25], s[20:21], exec
	s_cselect_b32 s5, s23, s27
	s_cselect_b32 s19, s22, s26
	s_ashr_i32 s17, s16, 31
	s_lshl_b64 s[24:25], s[16:17], 18
	s_add_u32 s17, s59, s24
	s_addc_u32 s25, s58, s25
	s_add_u32 s24, s17, s30
	s_addc_u32 s25, s25, s31
	s_and_b64 s[30:31], s[20:21], exec
	s_cselect_b32 s17, s25, s29
	s_cselect_b32 s58, s24, s28
	s_add_i32 s59, s57, -2
	s_add_u32 s26, s26, 0x20080
	s_addc_u32 s27, s27, 0
	s_add_u32 s60, s28, 0x100
	v_mov_b32_e32 v2, 0
	s_mov_b32 s62, 0
	s_addc_u32 s61, s29, 0
	v_mov_b32_e32 v3, v2
	v_mov_b32_e32 v4, v2
	v_mov_b32_e32 v5, v2
	v_mov_b32_e32 v6, v2
	v_mov_b32_e32 v7, v2
	v_mov_b32_e32 v8, v2
	v_mov_b32_e32 v9, v2
	v_mov_b32_e32 v10, v2
	v_mov_b32_e32 v11, v2
	v_mov_b32_e32 v12, v2
	v_mov_b32_e32 v13, v2
	v_mov_b32_e32 v14, v2
	v_mov_b32_e32 v15, v2
	v_mov_b32_e32 v16, v2
	v_mov_b32_e32 v17, v2
	v_mov_b32_e32 v22, v2
	v_mov_b32_e32 v23, v2
	v_mov_b32_e32 v24, v2
	v_mov_b32_e32 v25, v2
	v_mov_b32_e32 v30, v2
	v_mov_b32_e32 v31, v2
	v_mov_b32_e32 v32, v2
	v_mov_b32_e32 v33, v2
	v_mov_b32_e32 v38, v2
	v_mov_b32_e32 v39, v2
	v_mov_b32_e32 v40, v2
	v_mov_b32_e32 v41, v2
	v_mov_b32_e32 v46, v2
	v_mov_b32_e32 v47, v2
	v_mov_b32_e32 v48, v2
	v_mov_b32_e32 v49, v2
	v_mov_b32_e32 v18, v2
	v_mov_b32_e32 v19, v2
	v_mov_b32_e32 v20, v2
	v_mov_b32_e32 v21, v2
	v_mov_b32_e32 v26, v2
	v_mov_b32_e32 v27, v2
	v_mov_b32_e32 v28, v2
	v_mov_b32_e32 v29, v2
	v_mov_b32_e32 v34, v2
	v_mov_b32_e32 v35, v2
	v_mov_b32_e32 v36, v2
	v_mov_b32_e32 v37, v2
	v_mov_b32_e32 v42, v2
	v_mov_b32_e32 v43, v2
	v_mov_b32_e32 v44, v2
	v_mov_b32_e32 v45, v2
	v_mov_b32_e32 v50, v2
	v_mov_b32_e32 v51, v2
	v_mov_b32_e32 v52, v2
	v_mov_b32_e32 v53, v2
	v_mov_b32_e32 v54, v2
	v_mov_b32_e32 v55, v2
	v_mov_b32_e32 v56, v2
	v_mov_b32_e32 v57, v2
	v_mov_b32_e32 v58, v2
	v_mov_b32_e32 v59, v2
	v_mov_b32_e32 v60, v2
	v_mov_b32_e32 v61, v2
	v_mov_b32_e32 v62, v2
	v_mov_b32_e32 v63, v2
	v_mov_b32_e32 v64, v2
	v_mov_b32_e32 v65, v2
	v_mov_b32_e32 v66, v2
	v_mov_b32_e32 v67, v2
	v_mov_b32_e32 v68, v2
	v_mov_b32_e32 v69, v2
	v_mov_b32_e32 v70, v2
	v_mov_b32_e32 v71, v2
	v_mov_b32_e32 v72, v2
	v_mov_b32_e32 v73, v2
	v_mov_b32_e32 v74, v2
	v_mov_b32_e32 v75, v2
	v_mov_b32_e32 v76, v2
	v_mov_b32_e32 v77, v2
	v_mov_b32_e32 v78, v2
	v_mov_b32_e32 v79, v2
	v_mov_b32_e32 v80, v2
	v_mov_b32_e32 v81, v2
	v_mov_b32_e32 v86, v2
	v_mov_b32_e32 v87, v2
	v_mov_b32_e32 v88, v2
	v_mov_b32_e32 v89, v2
	v_mov_b32_e32 v94, v2
	v_mov_b32_e32 v95, v2
	v_mov_b32_e32 v96, v2
	v_mov_b32_e32 v97, v2
	v_mov_b32_e32 v102, v2
	v_mov_b32_e32 v103, v2
	v_mov_b32_e32 v104, v2
	v_mov_b32_e32 v105, v2
	v_mov_b32_e32 v110, v2
	v_mov_b32_e32 v111, v2
	v_mov_b32_e32 v112, v2
	v_mov_b32_e32 v113, v2
	v_mov_b32_e32 v82, v2
	v_mov_b32_e32 v83, v2
	v_mov_b32_e32 v84, v2
	v_mov_b32_e32 v85, v2
	v_mov_b32_e32 v90, v2
	v_mov_b32_e32 v91, v2
	v_mov_b32_e32 v92, v2
	v_mov_b32_e32 v93, v2
	v_mov_b32_e32 v98, v2
	v_mov_b32_e32 v99, v2
	v_mov_b32_e32 v100, v2
	v_mov_b32_e32 v101, v2
	v_mov_b32_e32 v106, v2
	v_mov_b32_e32 v107, v2
	v_mov_b32_e32 v108, v2
	v_mov_b32_e32 v109, v2
	v_mov_b32_e32 v114, v2
	v_mov_b32_e32 v115, v2
	v_mov_b32_e32 v116, v2
	v_mov_b32_e32 v117, v2
	v_mov_b32_e32 v118, v2
	v_mov_b32_e32 v119, v2
	v_mov_b32_e32 v120, v2
	v_mov_b32_e32 v121, v2
	v_mov_b32_e32 v122, v2
	v_mov_b32_e32 v123, v2
	v_mov_b32_e32 v124, v2
	v_mov_b32_e32 v125, v2
	v_mov_b32_e32 v126, v2
	v_mov_b32_e32 v127, v2
	v_mov_b32_e32 v128, v2
	v_mov_b32_e32 v129, v2
.LBB0_656:
	ds_read_b128 v[142:145], v158
	ds_read_b128 v[146:149], v158 offset:1024
	ds_read_b128 v[162:165], v158 offset:2048
	ds_read_b128 v[166:169], v158 offset:3072
	ds_read_b128 v[170:173], v159
	ds_read_b128 v[174:177], v159 offset:1024
	ds_read_b128 v[178:181], v159 offset:2048
	ds_read_b128 v[188:191], v159 offset:3072
	s_add_i32 s63, s62, 2
	s_add_u32 s28, s26, 0xfffe0080
	s_addc_u32 s29, s27, -1
	s_cmp_eq_u32 s59, s62
	s_cselect_b32 s31, s5, s29
	s_cselect_b32 s30, s19, s28
	s_cselect_b32 s29, s17, s61
	s_cselect_b32 s28, s58, s60
	v_lshl_add_u64 v[224:225], s[26:27], 0, v[136:137]
	s_add_i32 m0, s7, 0xc000
	ds_read_b128 v[192:195], v160
	ds_read_b128 v[196:199], v160 offset:1024
	ds_read_b128 v[200:203], v160 offset:2048
	ds_read_b128 v[204:207], v160 offset:3072
	ds_read_b128 v[208:211], v160 offset:4096
	ds_read_b128 v[212:215], v160 offset:5120
	ds_read_b128 v[216:219], v160 offset:6144
	ds_read_b128 v[220:223], v160 offset:7168
	global_load_lds_dwordx4 v[224:225], off
	v_lshl_add_u64 v[224:225], s[26:27], 0, v[138:139]
	s_add_i32 m0, s7, 0xe000
	s_nop 0
	global_load_lds_dwordx4 v[224:225], off
	s_cmp_eq_u32 s99, 0
	s_cbranch_scc1 .Lrx_GLU_s0
	s_waitcnt vmcnt(24)
	s_branch .Lrx_GLU_d0

; #define PG8_STAGE(bufoff, gbase) do { _Pragma("unroll") for (int _i = 0; _i < 2; ++_i) \
;         __builtin_amdgcn_global_load_lds((const unsigned*)((const char*)(gbase) + voff[_i]), (LAS unsigned*)(lds + (bufoff) + ldsw + _i * 8192), 16, 0, 0); } while (0)
; #define PG8_LDA(dst, b, h) do { _Pragma("unroll") for (int m = 0; m < 4; ++m) _Pragma("unroll") for (int k = 0; k < 2; ++k) dst[m][k] = *(const LAS bf16x8*)(lds + PG8_SA(b, h) + aoff + m * 2048 + k * 1024); } while (0)
; #define PG8_MMA(ai, bj, At, Bt) do { __builtin_amdgcn_s_setprio(1); _Pragma("unroll") for (int m = 0; m < 4; ++m) _Pragma("unroll") for (int n = 0; n < 2; ++n) _Pragma("unroll") for (int k = 0; k < 2; ++k) \
;         acc[ai][bj][m][n] = __builtin_amdgcn_mfma_f32_16x16x32_bf16(Bt[n][k], At[m][k], acc[ai][bj][m][n], 0, 0, 0); __builtin_amdgcn_s_setprio(0); } while (0)
; #define PG8_WAIT_V(n) asm volatile("s_waitcnt vmcnt(" #n ")" ::: "memory")
; #define PG8_WAIT_L(n) asm volatile("s_waitcnt lgkmcnt(" #n ")" ::: "memory")
; #define PG8_BAR __builtin_amdgcn_s_barrier()
; #define PG8_SCHED __builtin_amdgcn_sched_barrier(0)
; template <int EPI> ...
;     ...
;             PG8_WAIT_V(8); PG8_WAIT_L(0); PG8_BAR; PG8_MMA(0, 0, At, B0); PG8_MMA(0, 1, At, B1); PG8_BAR; PG8_SCHED;
;             PG8_LDA(At, 0, 1); PG8_STAGE(PG8_SB(0, 0), b2); PG8_STAGE(PG8_SB(0, 1), b2 + hstep); PG8_STAGE(PG8_SA(0, 0), a2);
.Lrx_GLU_d0:
	s_waitcnt lgkmcnt(0)
	s_barrier
	s_setprio 1
	s_waitcnt lgkmcnt(0)
	v_mfma_f32_16x16x32_bf16 v[126:129], v[142:145], v[192:195], v[126:129]
	v_mfma_f32_16x16x32_bf16 v[122:125], v[162:165], v[192:195], v[122:125]
	v_mfma_f32_16x16x32_bf16 v[118:121], v[142:145], v[200:203], v[118:121]
	v_mfma_f32_16x16x32_bf16 v[114:117], v[162:165], v[200:203], v[114:117]
	v_mfma_f32_16x16x32_bf16 v[106:109], v[142:145], v[208:211], v[106:109]
	v_mfma_f32_16x16x32_bf16 v[98:101], v[162:165], v[208:211], v[98:101]
	v_mfma_f32_16x16x32_bf16 v[90:93], v[142:145], v[216:219], v[90:93]
	v_mfma_f32_16x16x32_bf16 v[82:85], v[162:165], v[216:219], v[82:85]
	v_mfma_f32_16x16x32_bf16 v[126:129], v[146:149], v[196:199], v[126:129]
	v_mfma_f32_16x16x32_bf16 v[122:125], v[166:169], v[196:199], v[122:125]
	v_mfma_f32_16x16x32_bf16 v[118:121], v[146:149], v[204:207], v[118:121]
	v_mfma_f32_16x16x32_bf16 v[114:117], v[166:169], v[204:207], v[114:117]
	v_mfma_f32_16x16x32_bf16 v[106:109], v[146:149], v[212:215], v[106:109]
	v_mfma_f32_16x16x32_bf16 v[98:101], v[166:169], v[212:215], v[98:101]
	v_mfma_f32_16x16x32_bf16 v[90:93], v[146:149], v[220:223], v[90:93]
	v_mfma_f32_16x16x32_bf16 v[82:85], v[166:169], v[220:223], v[82:85]
	s_setprio 0
	s_setprio 1
	v_mfma_f32_16x16x32_bf16 v[110:113], v[170:173], v[192:195], v[110:113]
	v_mfma_f32_16x16x32_bf16 v[102:105], v[178:181], v[192:195], v[102:105]
	v_mfma_f32_16x16x32_bf16 v[94:97], v[170:173], v[200:203], v[94:97]
	v_mfma_f32_16x16x32_bf16 v[86:89], v[178:181], v[200:203], v[86:89]
	v_mfma_f32_16x16x32_bf16 v[78:81], v[170:173], v[208:211], v[78:81]
	v_mfma_f32_16x16x32_bf16 v[74:77], v[178:181], v[208:211], v[74:77]
	v_mfma_f32_16x16x32_bf16 v[70:73], v[170:173], v[216:219], v[70:73]
	v_mfma_f32_16x16x32_bf16 v[66:69], v[178:181], v[216:219], v[66:69]
	v_mfma_f32_16x16x32_bf16 v[110:113], v[174:177], v[196:199], v[110:113]
	v_mfma_f32_16x16x32_bf16 v[102:105], v[188:191], v[196:199], v[102:105]
	v_mfma_f32_16x16x32_bf16 v[94:97], v[174:177], v[204:207], v[94:97]
	v_mfma_f32_16x16x32_bf16 v[86:89], v[188:191], v[204:207], v[86:89]
	v_mfma_f32_16x16x32_bf16 v[78:81], v[174:177], v[212:215], v[78:81]
	v_mfma_f32_16x16x32_bf16 v[74:77], v[188:191], v[212:215], v[74:77]
	v_mfma_f32_16x16x32_bf16 v[70:73], v[174:177], v[220:223], v[70:73]
	v_mfma_f32_16x16x32_bf16 v[66:69], v[188:191], v[220:223], v[66:69]
	s_setprio 0
	s_barrier
	s_add_i32 s62, s48, s40
	v_lshl_add_u64 v[224:225], s[28:29], 0, v[130:131]
	s_mov_b32 m0, s62
	ds_read_b128 v[192:195], v160 offset:16384
	ds_read_b128 v[196:199], v160 offset:17408
	ds_read_b128 v[200:203], v160 offset:18432
	ds_read_b128 v[204:207], v160 offset:19456
	ds_read_b128 v[208:211], v160 offset:20480
	ds_read_b128 v[212:215], v160 offset:21504
	ds_read_b128 v[216:219], v160 offset:22528
	ds_read_b128 v[220:223], v160 offset:23552
	global_load_lds_dwordx4 v[224:225], off
	s_add_i32 m0, s62, 0x2000
	s_add_u32 s64, s28, 0x20000
	v_lshl_add_u64 v[226:227], s[28:29], 0, v[132:133]
	s_addc_u32 s65, s29, 0
	s_add_i32 s62, s49, s40
	global_load_lds_dwordx4 v[226:227], off
	v_lshl_add_u64 v[228:229], s[64:65], 0, v[130:131]
	s_mov_b32 m0, s62
	v_lshl_add_u64 v[230:231], s[30:31], 0, v[132:133]
	global_load_lds_dwordx4 v[228:229], off
	v_lshl_add_u64 v[228:229], s[64:65], 0, v[132:133]
	s_add_i32 m0, s62, 0x2000
	s_nop 0
	global_load_lds_dwordx4 v[228:229], off
	v_lshl_add_u64 v[228:229], s[30:31], 0, v[130:131]
	s_mov_b32 m0, s7
	s_nop 0
	global_load_lds_dwordx4 v[228:229], off
	s_mov_b32 m0, s42
	s_nop 0
	global_load_lds_dwordx4 v[230:231], off
	s_cmp_eq_u32 s99, 0
	s_cbranch_scc1 .Lrx_GLU_s1
	s_waitcnt vmcnt(24)
	s_branch .Lrx_GLU_d1

; #define PG8_STAGE(bufoff, gbase) do { _Pragma("unroll") for (int _i = 0; _i < 2; ++_i) \
;         __builtin_amdgcn_global_load_lds((const unsigned*)((const char*)(gbase) + voff[_i]), (LAS unsigned*)(lds + (bufoff) + ldsw + _i * 8192), 16, 0, 0); } while (0)
; #define PG8_LDA(dst, b, h) do { _Pragma("unroll") for (int m = 0; m < 4; ++m) _Pragma("unroll") for (int k = 0; k < 2; ++k) dst[m][k] = *(const LAS bf16x8*)(lds + PG8_SA(b, h) + aoff + m * 2048 + k * 1024); } while (0)
; #define PG8_LDB(dst, b, h) do { _Pragma("unroll") for (int n = 0; n < 2; ++n) _Pragma("unroll") for (int k = 0; k < 2; ++k) dst[n][k] = *(const LAS bf16x8*)(lds + PG8_SB(b, h) + boff + n * 2048 + k * 1024); } while (0)
; #define PG8_MMA(ai, bj, At, Bt) do { __builtin_amdgcn_s_setprio(1); _Pragma("unroll") for (int m = 0; m < 4; ++m) _Pragma("unroll") for (int n = 0; n < 2; ++n) _Pragma("unroll") for (int k = 0; k < 2; ++k) \
;         acc[ai][bj][m][n] = __builtin_amdgcn_mfma_f32_16x16x32_bf16(Bt[n][k], At[m][k], acc[ai][bj][m][n], 0, 0, 0); __builtin_amdgcn_s_setprio(0); } while (0)
; #define PG8_WAIT_V(n) asm volatile("s_waitcnt vmcnt(" #n ")" ::: "memory")
; #define PG8_WAIT_L(n) asm volatile("s_waitcnt lgkmcnt(" #n ")" ::: "memory")
; #define PG8_BAR __builtin_amdgcn_s_barrier()
; #define PG8_SCHED __builtin_amdgcn_sched_barrier(0)
; template <int EPI> ...
;     ...
;             PG8_LDA(At, 0, 1); PG8_STAGE(PG8_SB(0, 0), b2); PG8_STAGE(PG8_SB(0, 1), b2 + hstep); PG8_STAGE(PG8_SA(0, 0), a2);
;             PG8_WAIT_V(8); PG8_WAIT_L(0); PG8_BAR; PG8_MMA(1, 0, At, B0); PG8_MMA(1, 1, At, B1); PG8_BAR; PG8_SCHED;
;             PG8_LDB(B0, 1, 0); PG8_LDB(B1, 1, 1); PG8_SCHED; PG8_LDA(At, 1, 0); PG8_STAGE(PG8_SA(0, 1), a2 + hstep);
;             PG8_WAIT_V(8); PG8_WAIT_L(0); PG8_BAR; PG8_MMA(0, 0, At, B0); PG8_MMA(0, 1, At, B1); PG8_BAR; PG8_SCHED;
.Lrx_GLU_d1:
	s_mov_b32 s99, 0
	s_waitcnt lgkmcnt(0)
	s_barrier
	s_setprio 1
	s_waitcnt lgkmcnt(0)
	v_mfma_f32_16x16x32_bf16 v[62:65], v[142:145], v[192:195], v[62:65]
	v_mfma_f32_16x16x32_bf16 v[58:61], v[162:165], v[192:195], v[58:61]
	v_mfma_f32_16x16x32_bf16 v[54:57], v[142:145], v[200:203], v[54:57]
	v_mfma_f32_16x16x32_bf16 v[50:53], v[162:165], v[200:203], v[50:53]
	v_mfma_f32_16x16x32_bf16 v[42:45], v[142:145], v[208:211], v[42:45]
	v_mfma_f32_16x16x32_bf16 v[34:37], v[162:165], v[208:211], v[34:37]
	v_mfma_f32_16x16x32_bf16 v[26:29], v[142:145], v[216:219], v[26:29]
	v_mfma_f32_16x16x32_bf16 v[18:21], v[162:165], v[216:219], v[18:21]
	v_mfma_f32_16x16x32_bf16 v[62:65], v[146:149], v[196:199], v[62:65]
	v_mfma_f32_16x16x32_bf16 v[58:61], v[166:169], v[196:199], v[58:61]
	v_mfma_f32_16x16x32_bf16 v[54:57], v[146:149], v[204:207], v[54:57]
	v_mfma_f32_16x16x32_bf16 v[50:53], v[166:169], v[204:207], v[50:53]
	v_mfma_f32_16x16x32_bf16 v[42:45], v[146:149], v[212:215], v[42:45]
	v_mfma_f32_16x16x32_bf16 v[34:37], v[166:169], v[212:215], v[34:37]
	v_mfma_f32_16x16x32_bf16 v[26:29], v[146:149], v[220:223], v[26:29]
	v_mfma_f32_16x16x32_bf16 v[18:21], v[166:169], v[220:223], v[18:21]
	s_setprio 0
	s_setprio 1
	v_mfma_f32_16x16x32_bf16 v[46:49], v[170:173], v[192:195], v[46:49]
	v_mfma_f32_16x16x32_bf16 v[38:41], v[178:181], v[192:195], v[38:41]
	v_mfma_f32_16x16x32_bf16 v[30:33], v[170:173], v[200:203], v[30:33]
	v_mfma_f32_16x16x32_bf16 v[22:25], v[178:181], v[200:203], v[22:25]
	v_mfma_f32_16x16x32_bf16 v[14:17], v[170:173], v[208:211], v[14:17]
	v_mfma_f32_16x16x32_bf16 v[10:13], v[178:181], v[208:211], v[10:13]
	v_mfma_f32_16x16x32_bf16 v[6:9], v[170:173], v[216:219], v[6:9]
	v_mfma_f32_16x16x32_bf16 v[2:5], v[178:181], v[216:219], v[2:5]
	v_mfma_f32_16x16x32_bf16 v[46:49], v[174:177], v[196:199], v[46:49]
	v_mfma_f32_16x16x32_bf16 v[38:41], v[188:191], v[196:199], v[38:41]
	v_mfma_f32_16x16x32_bf16 v[30:33], v[174:177], v[204:207], v[30:33]
	v_mfma_f32_16x16x32_bf16 v[22:25], v[188:191], v[204:207], v[22:25]
	v_mfma_f32_16x16x32_bf16 v[14:17], v[174:177], v[212:215], v[14:17]
	v_mfma_f32_16x16x32_bf16 v[10:13], v[188:191], v[212:215], v[10:13]
	v_mfma_f32_16x16x32_bf16 v[6:9], v[174:177], v[220:223], v[6:9]
	v_mfma_f32_16x16x32_bf16 v[2:5], v[188:191], v[220:223], v[2:5]
	s_setprio 0
	s_barrier
	s_add_i32 s62, 0, 0x18000
	v_add_u32_e32 v134, s62, v152
	s_add_i32 s64, 0, 0x1c000
	ds_read_b128 v[142:145], v134
	ds_read_b128 v[146:149], v134 offset:1024
	ds_read_b128 v[162:165], v134 offset:2048
	ds_read_b128 v[166:169], v134 offset:3072
	v_add_u32_e32 v134, s64, v152
	ds_read_b128 v[170:173], v134
	ds_read_b128 v[174:177], v134 offset:1024
	ds_read_b128 v[178:181], v134 offset:2048
	ds_read_b128 v[188:191], v134 offset:3072
	s_add_u32 s30, s30, 0x20000
	s_addc_u32 s31, s31, 0
	s_mov_b32 m0, s43
	v_lshl_add_u64 v[232:233], s[30:31], 0, v[130:131]
	ds_read_b128 v[192:195], v160 offset:32768
	ds_read_b128 v[196:199], v160 offset:33792
	ds_read_b128 v[200:203], v160 offset:34816
	ds_read_b128 v[204:207], v160 offset:35840
	ds_read_b128 v[208:211], v160 offset:36864
	ds_read_b128 v[212:215], v160 offset:37888
	ds_read_b128 v[216:219], v160 offset:38912
	ds_read_b128 v[220:223], v160 offset:39936
	global_load_lds_dwordx4 v[232:233], off
	v_lshl_add_u64 v[232:233], s[30:31], 0, v[132:133]
	s_mov_b32 m0, s44
	s_nop 0
	global_load_lds_dwordx4 v[232:233], off
	s_waitcnt vmcnt(8)
	s_waitcnt lgkmcnt(0)
	s_barrier
	s_setprio 1
	s_waitcnt lgkmcnt(0)
	v_mfma_f32_16x16x32_bf16 v[126:129], v[142:145], v[192:195], v[126:129]
	v_mfma_f32_16x16x32_bf16 v[122:125], v[162:165], v[192:195], v[122:125]
	v_mfma_f32_16x16x32_bf16 v[118:121], v[142:145], v[200:203], v[118:121]
	v_mfma_f32_16x16x32_bf16 v[114:117], v[162:165], v[200:203], v[114:117]
	v_mfma_f32_16x16x32_bf16 v[106:109], v[142:145], v[208:211], v[106:109]
	v_mfma_f32_16x16x32_bf16 v[98:101], v[162:165], v[208:211], v[98:101]
	v_mfma_f32_16x16x32_bf16 v[90:93], v[142:145], v[216:219], v[90:93]
	v_mfma_f32_16x16x32_bf16 v[82:85], v[162:165], v[216:219], v[82:85]
	v_mfma_f32_16x16x32_bf16 v[126:129], v[146:149], v[196:199], v[126:129]
	v_mfma_f32_16x16x32_bf16 v[122:125], v[166:169], v[196:199], v[122:125]
	v_mfma_f32_16x16x32_bf16 v[118:121], v[146:149], v[204:207], v[118:121]
	v_mfma_f32_16x16x32_bf16 v[114:117], v[166:169], v[204:207], v[114:117]
	v_mfma_f32_16x16x32_bf16 v[106:109], v[146:149], v[212:215], v[106:109]
	v_mfma_f32_16x16x32_bf16 v[98:101], v[166:169], v[212:215], v[98:101]
	v_mfma_f32_16x16x32_bf16 v[90:93], v[146:149], v[220:223], v[90:93]
	v_mfma_f32_16x16x32_bf16 v[82:85], v[166:169], v[220:223], v[82:85]
	s_setprio 0
	s_setprio 1
	v_mfma_f32_16x16x32_bf16 v[110:113], v[170:173], v[192:195], v[110:113]
	v_mfma_f32_16x16x32_bf16 v[102:105], v[178:181], v[192:195], v[102:105]
	v_mfma_f32_16x16x32_bf16 v[94:97], v[170:173], v[200:203], v[94:97]
	v_mfma_f32_16x16x32_bf16 v[86:89], v[178:181], v[200:203], v[86:89]
	v_mfma_f32_16x16x32_bf16 v[78:81], v[170:173], v[208:211], v[78:81]
	v_mfma_f32_16x16x32_bf16 v[74:77], v[178:181], v[208:211], v[74:77]
	v_mfma_f32_16x16x32_bf16 v[70:73], v[170:173], v[216:219], v[70:73]
	v_mfma_f32_16x16x32_bf16 v[66:69], v[178:181], v[216:219], v[66:69]
	v_mfma_f32_16x16x32_bf16 v[110:113], v[174:177], v[196:199], v[110:113]
	v_mfma_f32_16x16x32_bf16 v[102:105], v[188:191], v[196:199], v[102:105]
	v_mfma_f32_16x16x32_bf16 v[94:97], v[174:177], v[204:207], v[94:97]
	v_mfma_f32_16x16x32_bf16 v[86:89], v[188:191], v[204:207], v[86:89]
	v_mfma_f32_16x16x32_bf16 v[78:81], v[174:177], v[212:215], v[78:81]
	v_mfma_f32_16x16x32_bf16 v[74:77], v[188:191], v[212:215], v[74:77]
	v_mfma_f32_16x16x32_bf16 v[70:73], v[174:177], v[220:223], v[70:73]
	v_mfma_f32_16x16x32_bf16 v[66:69], v[188:191], v[220:223], v[66:69]
	s_setprio 0
	s_barrier
; #define PG8_STAGE(bufoff, gbase) do { _Pragma("unroll") for (int _i = 0; _i < 2; ++_i) \
;         __builtin_amdgcn_global_load_lds((const unsigned*)((const char*)(gbase) + voff[_i]), (LAS unsigned*)(lds + (bufoff) + ldsw + _i * 8192), 16, 0, 0); } while (0)
; #define PG8_LDA(dst, b, h) do { _Pragma("unroll") for (int m = 0; m < 4; ++m) _Pragma("unroll") for (int k = 0; k < 2; ++k) dst[m][k] = *(const LAS bf16x8*)(lds + PG8_SA(b, h) + aoff + m * 2048 + k * 1024); } while (0)
; #define PG8_MMA(ai, bj, At, Bt) do { __builtin_amdgcn_s_setprio(1); _Pragma("unroll") for (int m = 0; m < 4; ++m) _Pragma("unroll") for (int n = 0; n < 2; ++n) _Pragma("unroll") for (int k = 0; k < 2; ++k) \
;         acc[ai][bj][m][n] = __builtin_amdgcn_mfma_f32_16x16x32_bf16(Bt[n][k], At[m][k], acc[ai][bj][m][n], 0, 0, 0); __builtin_amdgcn_s_setprio(0); } while (0)
; #define PG8_WAIT_V(n) asm volatile("s_waitcnt vmcnt(" #n ")" ::: "memory")
; #define PG8_WAIT_L(n) asm volatile("s_waitcnt lgkmcnt(" #n ")" ::: "memory")
; #define PG8_BAR __builtin_amdgcn_s_barrier()
; #define PG8_SCHED __builtin_amdgcn_sched_barrier(0)
; template <int EPI> ...
;     ...
;             PG8_LDA(At, 1, 1); PG8_STAGE(PG8_SB(1, 0), b3); PG8_STAGE(PG8_SB(1, 1), b3 + hstep); PG8_STAGE(PG8_SA(1, 0), a3);
;             PG8_WAIT_V(8); PG8_WAIT_L(0); PG8_BAR; PG8_MMA(1, 0, At, B0); PG8_MMA(1, 1, At, B1); PG8_BAR; PG8_SCHED;
;         }
;         if (wr == 0) PG8_BAR;
;         if (SPLIT && cur_slice >= 0) {
	s_add_i32 s30, s62, s40
	v_lshl_add_u64 v[224:225], v[224:225], 0, s[10:11]
	s_mov_b32 m0, s30
	ds_read_b128 v[192:195], v160 offset:49152
	ds_read_b128 v[196:199], v160 offset:50176
	ds_read_b128 v[200:203], v160 offset:51200
	ds_read_b128 v[204:207], v160 offset:52224
	ds_read_b128 v[208:211], v160 offset:53248
	ds_read_b128 v[212:215], v160 offset:54272
	ds_read_b128 v[216:219], v160 offset:55296
	ds_read_b128 v[220:223], v160 offset:56320
	global_load_lds_dwordx4 v[224:225], off
	s_add_i32 m0, s30, 0x2000
	s_add_u32 s28, s28, 0x20080
	v_lshl_add_u64 v[224:225], v[226:227], 0, s[10:11]
	s_addc_u32 s29, s29, 0
	s_add_i32 s30, s64, s40
	global_load_lds_dwordx4 v[224:225], off
	v_lshl_add_u64 v[224:225], s[28:29], 0, v[130:131]
	s_mov_b32 m0, s30
	s_nop 0
	global_load_lds_dwordx4 v[224:225], off
	v_lshl_add_u64 v[224:225], s[28:29], 0, v[132:133]
	s_add_i32 m0, s30, 0x2000
	s_nop 0
	global_load_lds_dwordx4 v[224:225], off
	v_lshl_add_u64 v[224:225], v[228:229], 0, s[10:11]
	s_mov_b32 m0, s45
	s_nop 0
	global_load_lds_dwordx4 v[224:225], off
	v_lshl_add_u64 v[224:225], v[230:231], 0, s[10:11]
	s_mov_b32 m0, s46
	s_nop 0
	global_load_lds_dwordx4 v[224:225], off
	s_waitcnt vmcnt(8)
	s_waitcnt lgkmcnt(0)
	s_barrier
	s_setprio 1
	s_waitcnt lgkmcnt(0)
	v_mfma_f32_16x16x32_bf16 v[62:65], v[142:145], v[192:195], v[62:65]
	v_mfma_f32_16x16x32_bf16 v[58:61], v[162:165], v[192:195], v[58:61]
	v_mfma_f32_16x16x32_bf16 v[54:57], v[142:145], v[200:203], v[54:57]
	v_mfma_f32_16x16x32_bf16 v[50:53], v[162:165], v[200:203], v[50:53]
	v_mfma_f32_16x16x32_bf16 v[42:45], v[142:145], v[208:211], v[42:45]
	v_mfma_f32_16x16x32_bf16 v[34:37], v[162:165], v[208:211], v[34:37]
	v_mfma_f32_16x16x32_bf16 v[26:29], v[142:145], v[216:219], v[26:29]
	v_mfma_f32_16x16x32_bf16 v[18:21], v[162:165], v[216:219], v[18:21]
	v_mfma_f32_16x16x32_bf16 v[62:65], v[146:149], v[196:199], v[62:65]
	v_mfma_f32_16x16x32_bf16 v[58:61], v[166:169], v[196:199], v[58:61]
	v_mfma_f32_16x16x32_bf16 v[54:57], v[146:149], v[204:207], v[54:57]
	v_mfma_f32_16x16x32_bf16 v[50:53], v[166:169], v[204:207], v[50:53]
	v_mfma_f32_16x16x32_bf16 v[42:45], v[146:149], v[212:215], v[42:45]
	v_mfma_f32_16x16x32_bf16 v[34:37], v[166:169], v[212:215], v[34:37]
	v_mfma_f32_16x16x32_bf16 v[26:29], v[146:149], v[220:223], v[26:29]
	v_mfma_f32_16x16x32_bf16 v[18:21], v[166:169], v[220:223], v[18:21]
	s_setprio 0
	s_setprio 1
	v_mfma_f32_16x16x32_bf16 v[46:49], v[170:173], v[192:195], v[46:49]
	v_mfma_f32_16x16x32_bf16 v[38:41], v[178:181], v[192:195], v[38:41]
	v_mfma_f32_16x16x32_bf16 v[30:33], v[170:173], v[200:203], v[30:33]
	v_mfma_f32_16x16x32_bf16 v[22:25], v[178:181], v[200:203], v[22:25]
	v_mfma_f32_16x16x32_bf16 v[14:17], v[170:173], v[208:211], v[14:17]
	v_mfma_f32_16x16x32_bf16 v[10:13], v[178:181], v[208:211], v[10:13]
	v_mfma_f32_16x16x32_bf16 v[6:9], v[170:173], v[216:219], v[6:9]
	v_mfma_f32_16x16x32_bf16 v[2:5], v[178:181], v[216:219], v[2:5]
	v_mfma_f32_16x16x32_bf16 v[46:49], v[174:177], v[196:199], v[46:49]
	v_mfma_f32_16x16x32_bf16 v[38:41], v[188:191], v[196:199], v[38:41]
	v_mfma_f32_16x16x32_bf16 v[30:33], v[174:177], v[204:207], v[30:33]
	v_mfma_f32_16x16x32_bf16 v[22:25], v[188:191], v[204:207], v[22:25]
	v_mfma_f32_16x16x32_bf16 v[14:17], v[174:177], v[212:215], v[14:17]
	v_mfma_f32_16x16x32_bf16 v[10:13], v[188:191], v[212:215], v[10:13]
	v_mfma_f32_16x16x32_bf16 v[6:9], v[174:177], v[220:223], v[6:9]
	v_mfma_f32_16x16x32_bf16 v[2:5], v[188:191], v[220:223], v[2:5]
	s_setprio 0
	s_barrier
	s_add_u32 s26, s26, 0x100
	s_addc_u32 s27, s27, 0
	s_add_u32 s60, s60, 0x100
	s_addc_u32 s61, s61, 0
	s_cmp_ge_u32 s63, s57
	s_mov_b32 s62, s63
	s_cbranch_scc0 .LBB0_656
	s_mov_b32 s99, 1
	s_and_b64 vcc, exec, s[12:13]
	s_cbranch_vccz .LBB0_661
	s_barrier
	s_cmp_lt_i32 s0, 0
	s_mov_b64 s[26:27], -1
	s_cbranch_scc1 .LBB0_662

;     __device__ __forceinline__ bool next(int i, int& pm, int& pn, int& k0, int& nk, int& slice, int& src) const {
;     ...
;         if (nsplit == 0) return false;
;         int sidx = (int)(L - nwg);
;         if (sidx >= nslice_items) return false;
;         int ncol = nN;
;         if (glu && sidx >= 64) { sidx -= 64; src = 1; ncol = 4; }
;         const int tl = sidx / nsplit; slice = sidx - tl * nsplit; pm = 64 + tl / ncol; pn = tl % ncol; nk = nt / nsplit; k0 = slice * nk; return true;
.LBB0_799:
	s_or_b64 exec, exec, s[0:1]
	v_readlane_b32 s0, v244, 62
	v_mov_b32_e32 v10, v0
	v_readlane_b32 s1, v244, 63
	s_waitcnt lgkmcnt(0)
	s_barrier
	s_mov_b32 s99, 0
	s_and_b64 vcc, exec, s[0:1]
	v_readfirstlane_b32 s14, v10
	s_cbranch_vccz .LBB0_802
	v_readlane_b32 s5, v244, 33
	s_cmpk_lt_u32 s5, 0x140
	s_mov_b64 s[12:13], 0
	s_cbranch_scc0 .LBB0_803
	s_add_i32 s1, s5, 0xffffff00
	s_and_b32 s0, s5, 7
	s_lshr_b32 s1, s1, 5
	s_add_i32 s4, s1, 64
	s_bfe_u32 s6, s5, 0x20003
	s_lshl_b32 s8, s0, 8
	s_mov_b32 s9, 0
	s_mov_b64 s[10:11], -1
	s_mov_b32 s52, 2
	s_and_b64 vcc, exec, s[12:13]
	s_cbranch_vccnz .LBB0_804
	s_branch .LBB0_809

; #define PG8_STAGE(bufoff, gbase) do { _Pragma("unroll") for (int _i = 0; _i < 2; ++_i) \
;         __builtin_amdgcn_global_load_lds((const unsigned*)((const char*)(gbase) + voff[_i]), (LAS unsigned*)(lds + (bufoff) + ldsw + _i * 8192), 16, 0, 0); } while (0)
; #define PG8_LDA(dst, b, h) do { _Pragma("unroll") for (int m = 0; m < 4; ++m) _Pragma("unroll") for (int k = 0; k < 2; ++k) dst[m][k] = *(const LAS bf16x8*)(lds + PG8_SA(b, h) + aoff + m * 2048 + k * 1024); } while (0)
; #define PG8_LDB(dst, b, h) do { _Pragma("unroll") for (int n = 0; n < 2; ++n) _Pragma("unroll") for (int k = 0; k < 2; ++k) dst[n][k] = *(const LAS bf16x8*)(lds + PG8_SB(b, h) + boff + n * 2048 + k * 1024); } while (0)
; #define PG8_MMA(ai, bj, At, Bt) do { __builtin_amdgcn_s_setprio(1); _Pragma("unroll") for (int m = 0; m < 4; ++m) _Pragma("unroll") for (int n = 0; n < 2; ++n) _Pragma("unroll") for (int k = 0; k < 2; ++k) \
;         acc[ai][bj][m][n] = __builtin_amdgcn_mfma_f32_16x16x32_bf16(Bt[n][k], At[m][k], acc[ai][bj][m][n], 0, 0, 0); __builtin_amdgcn_s_setprio(0); } while (0)
; #define PG8_WAIT_V(n) asm volatile("s_waitcnt vmcnt(" #n ")" ::: "memory")
; #define PG8_WAIT_L(n) asm volatile("s_waitcnt lgkmcnt(" #n ")" ::: "memory")
; #define PG8_BAR __builtin_amdgcn_s_barrier()
; #define PG8_SCHED __builtin_amdgcn_sched_barrier(0)
; template <int EPI> ...
;     ...
;         for (int t = 0; t < cnk; t += 2) {
;             const bool last = (t == cnk - 2);
;             const char* a1 = cA + (size_t)(t + 1) * kstep;
;             const char* a2 = last ? nA : cA + (size_t)(t + 2) * kstep; const char* b2 = last ? nB : cB + (size_t)(t + 2) * kstep;
;             const char* a3 = a2 + kstep; const char* b3 = b2 + kstep;
;             PG8_LDB(B0, 0, 0); PG8_LDB(B1, 0, 1); PG8_SCHED; PG8_LDA(At, 0, 0); PG8_STAGE(PG8_SA(1, 1), a1 + hstep);
;             PG8_WAIT_V(8); PG8_WAIT_L(0); PG8_BAR; PG8_MMA(0, 0, At, B0); PG8_MMA(0, 1, At, B1); PG8_BAR; PG8_SCHED;
.LBB0_825:
	ds_read_b128 v[142:145], v152
	ds_read_b128 v[156:159], v152 offset:1024
	ds_read_b128 v[160:163], v152 offset:2048
	ds_read_b128 v[164:167], v152 offset:3072
	ds_read_b128 v[168:171], v153
	ds_read_b128 v[172:175], v153 offset:1024
	ds_read_b128 v[176:179], v153 offset:2048
	ds_read_b128 v[188:191], v153 offset:3072
	s_add_i32 s57, s34, 2
	s_add_u32 s35, s30, 0xfffc0080
	s_addc_u32 s36, s31, -1
	s_cmp_eq_u32 s54, s34
	s_cselect_b32 s34, s53, s55
	s_cselect_b32 s37, s5, s36
	s_cselect_b32 s36, s19, s35
	s_cselect_b32 s35, s17, s56
	v_lshl_add_u64 v[146:147], s[30:31], 0, v[136:137]
	s_add_i32 m0, s7, 0xc000
	ds_read_b128 v[192:195], v154
	ds_read_b128 v[196:199], v154 offset:1024
	ds_read_b128 v[200:203], v154 offset:2048
	ds_read_b128 v[204:207], v154 offset:3072
	ds_read_b128 v[208:211], v154 offset:4096
	ds_read_b128 v[212:215], v154 offset:5120
	ds_read_b128 v[216:219], v154 offset:6144
	ds_read_b128 v[220:223], v154 offset:7168
	global_load_lds_dwordx4 v[146:147], off
	v_lshl_add_u64 v[146:147], s[30:31], 0, v[138:139]
	s_add_i32 m0, s7, 0xe000
	s_nop 0
	global_load_lds_dwordx4 v[146:147], off
	s_cmp_eq_u32 s99, 0
	s_cbranch_scc1 .Lrx_WO_s0
	s_waitcnt vmcnt(40)
	s_branch .Lrx_WO_d0

; #define PG8_STAGE(bufoff, gbase) do { _Pragma("unroll") for (int _i = 0; _i < 2; ++_i) \
;         __builtin_amdgcn_global_load_lds((const unsigned*)((const char*)(gbase) + voff[_i]), (LAS unsigned*)(lds + (bufoff) + ldsw + _i * 8192), 16, 0, 0); } while (0)
; #define PG8_LDA(dst, b, h) do { _Pragma("unroll") for (int m = 0; m < 4; ++m) _Pragma("unroll") for (int k = 0; k < 2; ++k) dst[m][k] = *(const LAS bf16x8*)(lds + PG8_SA(b, h) + aoff + m * 2048 + k * 1024); } while (0)
; #define PG8_MMA(ai, bj, At, Bt) do { __builtin_amdgcn_s_setprio(1); _Pragma("unroll") for (int m = 0; m < 4; ++m) _Pragma("unroll") for (int n = 0; n < 2; ++n) _Pragma("unroll") for (int k = 0; k < 2; ++k) \
;         acc[ai][bj][m][n] = __builtin_amdgcn_mfma_f32_16x16x32_bf16(Bt[n][k], At[m][k], acc[ai][bj][m][n], 0, 0, 0); __builtin_amdgcn_s_setprio(0); } while (0)
; #define PG8_WAIT_V(n) asm volatile("s_waitcnt vmcnt(" #n ")" ::: "memory")
; #define PG8_WAIT_L(n) asm volatile("s_waitcnt lgkmcnt(" #n ")" ::: "memory")
; #define PG8_BAR __builtin_amdgcn_s_barrier()
; #define PG8_SCHED __builtin_amdgcn_sched_barrier(0)
; template <int EPI> ...
;     ...
;             PG8_WAIT_V(8); PG8_WAIT_L(0); PG8_BAR; PG8_MMA(0, 0, At, B0); PG8_MMA(0, 1, At, B1); PG8_BAR; PG8_SCHED;
;             PG8_LDA(At, 0, 1); PG8_STAGE(PG8_SB(0, 0), b2); PG8_STAGE(PG8_SB(0, 1), b2 + hstep); PG8_STAGE(PG8_SA(0, 0), a2);
.Lrx_WO_d0:
	s_waitcnt lgkmcnt(0)
	s_barrier
	s_setprio 1
	s_waitcnt lgkmcnt(0)
	v_mfma_f32_16x16x32_bf16 v[126:129], v[142:145], v[192:195], v[126:129]
	v_mfma_f32_16x16x32_bf16 v[122:125], v[160:163], v[192:195], v[122:125]
	v_mfma_f32_16x16x32_bf16 v[118:121], v[142:145], v[200:203], v[118:121]
	v_mfma_f32_16x16x32_bf16 v[114:117], v[160:163], v[200:203], v[114:117]
	v_mfma_f32_16x16x32_bf16 v[106:109], v[142:145], v[208:211], v[106:109]
	v_mfma_f32_16x16x32_bf16 v[98:101], v[160:163], v[208:211], v[98:101]
	v_mfma_f32_16x16x32_bf16 v[90:93], v[142:145], v[216:219], v[90:93]
	v_mfma_f32_16x16x32_bf16 v[82:85], v[160:163], v[216:219], v[82:85]
	v_mfma_f32_16x16x32_bf16 v[126:129], v[156:159], v[196:199], v[126:129]
	v_mfma_f32_16x16x32_bf16 v[122:125], v[164:167], v[196:199], v[122:125]
	v_mfma_f32_16x16x32_bf16 v[118:121], v[156:159], v[204:207], v[118:121]
	v_mfma_f32_16x16x32_bf16 v[114:117], v[164:167], v[204:207], v[114:117]
	v_mfma_f32_16x16x32_bf16 v[106:109], v[156:159], v[212:215], v[106:109]
	v_mfma_f32_16x16x32_bf16 v[98:101], v[164:167], v[212:215], v[98:101]
	v_mfma_f32_16x16x32_bf16 v[90:93], v[156:159], v[220:223], v[90:93]
	v_mfma_f32_16x16x32_bf16 v[82:85], v[164:167], v[220:223], v[82:85]
	s_setprio 0
	s_setprio 1
	v_mfma_f32_16x16x32_bf16 v[110:113], v[168:171], v[192:195], v[110:113]
	v_mfma_f32_16x16x32_bf16 v[102:105], v[176:179], v[192:195], v[102:105]
	v_mfma_f32_16x16x32_bf16 v[94:97], v[168:171], v[200:203], v[94:97]
	v_mfma_f32_16x16x32_bf16 v[86:89], v[176:179], v[200:203], v[86:89]
	v_mfma_f32_16x16x32_bf16 v[78:81], v[168:171], v[208:211], v[78:81]
	v_mfma_f32_16x16x32_bf16 v[74:77], v[176:179], v[208:211], v[74:77]
	v_mfma_f32_16x16x32_bf16 v[70:73], v[168:171], v[216:219], v[70:73]
	v_mfma_f32_16x16x32_bf16 v[66:69], v[176:179], v[216:219], v[66:69]
	v_mfma_f32_16x16x32_bf16 v[110:113], v[172:175], v[196:199], v[110:113]
	v_mfma_f32_16x16x32_bf16 v[102:105], v[188:191], v[196:199], v[102:105]
	v_mfma_f32_16x16x32_bf16 v[94:97], v[172:175], v[204:207], v[94:97]
	v_mfma_f32_16x16x32_bf16 v[86:89], v[188:191], v[204:207], v[86:89]
	v_mfma_f32_16x16x32_bf16 v[78:81], v[172:175], v[212:215], v[78:81]
	v_mfma_f32_16x16x32_bf16 v[74:77], v[188:191], v[212:215], v[74:77]
	v_mfma_f32_16x16x32_bf16 v[70:73], v[172:175], v[220:223], v[70:73]
	v_mfma_f32_16x16x32_bf16 v[66:69], v[188:191], v[220:223], v[66:69]
	s_setprio 0
	s_barrier
	s_add_i32 s58, s46, s39
	v_lshl_add_u64 v[146:147], s[34:35], 0, v[130:131]
	s_mov_b32 m0, s58
	ds_read_b128 v[192:195], v154 offset:16384
	ds_read_b128 v[196:199], v154 offset:17408
	ds_read_b128 v[200:203], v154 offset:18432
	ds_read_b128 v[204:207], v154 offset:19456
	ds_read_b128 v[208:211], v154 offset:20480
	ds_read_b128 v[212:215], v154 offset:21504
	ds_read_b128 v[216:219], v154 offset:22528
	ds_read_b128 v[220:223], v154 offset:23552
	global_load_lds_dwordx4 v[146:147], off
	s_add_i32 m0, s58, 0x2000
	s_add_u32 s58, s34, 0x40000
	v_lshl_add_u64 v[180:181], s[34:35], 0, v[132:133]
	s_addc_u32 s59, s35, 0
	s_add_i32 s60, s47, s39
	global_load_lds_dwordx4 v[180:181], off
	v_lshl_add_u64 v[224:225], s[58:59], 0, v[130:131]
	s_mov_b32 m0, s60
	v_lshl_add_u64 v[226:227], s[36:37], 0, v[132:133]
	global_load_lds_dwordx4 v[224:225], off
	v_lshl_add_u64 v[224:225], s[58:59], 0, v[132:133]
	s_add_i32 m0, s60, 0x2000
	s_nop 0
	global_load_lds_dwordx4 v[224:225], off
	v_lshl_add_u64 v[224:225], s[36:37], 0, v[130:131]
	s_mov_b32 m0, s7
	s_nop 0
	global_load_lds_dwordx4 v[224:225], off
	s_mov_b32 m0, s40
	s_nop 0
	global_load_lds_dwordx4 v[226:227], off
	s_cmp_eq_u32 s99, 0
	s_cbranch_scc1 .Lrx_WO_s1
	s_waitcnt vmcnt(40)
	s_branch .Lrx_WO_d1

; #define PG8_STAGE(bufoff, gbase) do { _Pragma("unroll") for (int _i = 0; _i < 2; ++_i) \
;         __builtin_amdgcn_global_load_lds((const unsigned*)((const char*)(gbase) + voff[_i]), (LAS unsigned*)(lds + (bufoff) + ldsw + _i * 8192), 16, 0, 0); } while (0)
; #define PG8_LDA(dst, b, h) do { _Pragma("unroll") for (int m = 0; m < 4; ++m) _Pragma("unroll") for (int k = 0; k < 2; ++k) dst[m][k] = *(const LAS bf16x8*)(lds + PG8_SA(b, h) + aoff + m * 2048 + k * 1024); } while (0)
; #define PG8_LDB(dst, b, h) do { _Pragma("unroll") for (int n = 0; n < 2; ++n) _Pragma("unroll") for (int k = 0; k < 2; ++k) dst[n][k] = *(const LAS bf16x8*)(lds + PG8_SB(b, h) + boff + n * 2048 + k * 1024); } while (0)
; #define PG8_MMA(ai, bj, At, Bt) do { __builtin_amdgcn_s_setprio(1); _Pragma("unroll") for (int m = 0; m < 4; ++m) _Pragma("unroll") for (int n = 0; n < 2; ++n) _Pragma("unroll") for (int k = 0; k < 2; ++k) \
;         acc[ai][bj][m][n] = __builtin_amdgcn_mfma_f32_16x16x32_bf16(Bt[n][k], At[m][k], acc[ai][bj][m][n], 0, 0, 0); __builtin_amdgcn_s_setprio(0); } while (0)
; #define PG8_WAIT_V(n) asm volatile("s_waitcnt vmcnt(" #n ")" ::: "memory")
; #define PG8_WAIT_L(n) asm volatile("s_waitcnt lgkmcnt(" #n ")" ::: "memory")
; #define PG8_BAR __builtin_amdgcn_s_barrier()
; #define PG8_SCHED __builtin_amdgcn_sched_barrier(0)
; template <int EPI> ...
;     ...
;             PG8_LDA(At, 0, 1); PG8_STAGE(PG8_SB(0, 0), b2); PG8_STAGE(PG8_SB(0, 1), b2 + hstep); PG8_STAGE(PG8_SA(0, 0), a2);
;             PG8_WAIT_V(8); PG8_WAIT_L(0); PG8_BAR; PG8_MMA(1, 0, At, B0); PG8_MMA(1, 1, At, B1); PG8_BAR; PG8_SCHED;
;             PG8_LDB(B0, 1, 0); PG8_LDB(B1, 1, 1); PG8_SCHED; PG8_LDA(At, 1, 0); PG8_STAGE(PG8_SA(0, 1), a2 + hstep);
;             PG8_WAIT_V(8); PG8_WAIT_L(0); PG8_BAR; PG8_MMA(0, 0, At, B0); PG8_MMA(0, 1, At, B1); PG8_BAR; PG8_SCHED;
.Lrx_WO_d1:
	s_mov_b32 s99, 0
	s_waitcnt lgkmcnt(0)
	s_barrier
	s_setprio 1
	s_waitcnt lgkmcnt(0)
	v_mfma_f32_16x16x32_bf16 v[62:65], v[142:145], v[192:195], v[62:65]
	v_mfma_f32_16x16x32_bf16 v[58:61], v[160:163], v[192:195], v[58:61]
	v_mfma_f32_16x16x32_bf16 v[54:57], v[142:145], v[200:203], v[54:57]
	v_mfma_f32_16x16x32_bf16 v[50:53], v[160:163], v[200:203], v[50:53]
	v_mfma_f32_16x16x32_bf16 v[42:45], v[142:145], v[208:211], v[42:45]
	v_mfma_f32_16x16x32_bf16 v[34:37], v[160:163], v[208:211], v[34:37]
	v_mfma_f32_16x16x32_bf16 v[26:29], v[142:145], v[216:219], v[26:29]
	v_mfma_f32_16x16x32_bf16 v[18:21], v[160:163], v[216:219], v[18:21]
	v_mfma_f32_16x16x32_bf16 v[62:65], v[156:159], v[196:199], v[62:65]
	v_mfma_f32_16x16x32_bf16 v[58:61], v[164:167], v[196:199], v[58:61]
	v_mfma_f32_16x16x32_bf16 v[54:57], v[156:159], v[204:207], v[54:57]
	v_mfma_f32_16x16x32_bf16 v[50:53], v[164:167], v[204:207], v[50:53]
	v_mfma_f32_16x16x32_bf16 v[42:45], v[156:159], v[212:215], v[42:45]
	v_mfma_f32_16x16x32_bf16 v[34:37], v[164:167], v[212:215], v[34:37]
	v_mfma_f32_16x16x32_bf16 v[26:29], v[156:159], v[220:223], v[26:29]
	v_mfma_f32_16x16x32_bf16 v[18:21], v[164:167], v[220:223], v[18:21]
	s_setprio 0
	s_setprio 1
	v_mfma_f32_16x16x32_bf16 v[46:49], v[168:171], v[192:195], v[46:49]
	v_mfma_f32_16x16x32_bf16 v[38:41], v[176:179], v[192:195], v[38:41]
	v_mfma_f32_16x16x32_bf16 v[30:33], v[168:171], v[200:203], v[30:33]
	v_mfma_f32_16x16x32_bf16 v[22:25], v[176:179], v[200:203], v[22:25]
	v_mfma_f32_16x16x32_bf16 v[14:17], v[168:171], v[208:211], v[14:17]
	v_mfma_f32_16x16x32_bf16 v[10:13], v[176:179], v[208:211], v[10:13]
	v_mfma_f32_16x16x32_bf16 v[6:9], v[168:171], v[216:219], v[6:9]
	v_mfma_f32_16x16x32_bf16 v[2:5], v[176:179], v[216:219], v[2:5]
	v_mfma_f32_16x16x32_bf16 v[46:49], v[172:175], v[196:199], v[46:49]
	v_mfma_f32_16x16x32_bf16 v[38:41], v[188:191], v[196:199], v[38:41]
	v_mfma_f32_16x16x32_bf16 v[30:33], v[172:175], v[204:207], v[30:33]
	v_mfma_f32_16x16x32_bf16 v[22:25], v[188:191], v[204:207], v[22:25]
	v_mfma_f32_16x16x32_bf16 v[14:17], v[172:175], v[212:215], v[14:17]
	v_mfma_f32_16x16x32_bf16 v[10:13], v[188:191], v[212:215], v[10:13]
	v_mfma_f32_16x16x32_bf16 v[6:9], v[172:175], v[220:223], v[6:9]
	v_mfma_f32_16x16x32_bf16 v[2:5], v[188:191], v[220:223], v[2:5]
	s_setprio 0
	s_barrier
	s_add_i32 s58, 0, 0x18000
	v_add_u32_e32 v155, s58, v149
	s_add_i32 s59, 0, 0x1c000
	ds_read_b128 v[142:145], v155
	ds_read_b128 v[156:159], v155 offset:1024
	ds_read_b128 v[160:163], v155 offset:2048
	ds_read_b128 v[164:167], v155 offset:3072
	v_add_u32_e32 v155, s59, v149
	ds_read_b128 v[168:171], v155
	ds_read_b128 v[172:175], v155 offset:1024
	ds_read_b128 v[176:179], v155 offset:2048
	ds_read_b128 v[188:191], v155 offset:3072
	s_add_u32 s36, s36, 0x40000
	s_addc_u32 s37, s37, 0
	s_mov_b32 m0, s41
	v_lshl_add_u64 v[228:229], s[36:37], 0, v[130:131]
	ds_read_b128 v[192:195], v154 offset:32768
	ds_read_b128 v[196:199], v154 offset:33792
	ds_read_b128 v[200:203], v154 offset:34816
	ds_read_b128 v[204:207], v154 offset:35840
	ds_read_b128 v[208:211], v154 offset:36864
	ds_read_b128 v[212:215], v154 offset:37888
	ds_read_b128 v[216:219], v154 offset:38912
	ds_read_b128 v[220:223], v154 offset:39936
	global_load_lds_dwordx4 v[228:229], off
	v_lshl_add_u64 v[228:229], s[36:37], 0, v[132:133]
	s_mov_b32 m0, s42
	s_nop 0
	global_load_lds_dwordx4 v[228:229], off
	s_waitcnt vmcnt(8)
	s_waitcnt lgkmcnt(0)
	s_barrier
	s_setprio 1
	s_waitcnt lgkmcnt(0)
	v_mfma_f32_16x16x32_bf16 v[126:129], v[142:145], v[192:195], v[126:129]
	v_mfma_f32_16x16x32_bf16 v[122:125], v[160:163], v[192:195], v[122:125]
	v_mfma_f32_16x16x32_bf16 v[118:121], v[142:145], v[200:203], v[118:121]
	v_mfma_f32_16x16x32_bf16 v[114:117], v[160:163], v[200:203], v[114:117]
	v_mfma_f32_16x16x32_bf16 v[106:109], v[142:145], v[208:211], v[106:109]
	v_mfma_f32_16x16x32_bf16 v[98:101], v[160:163], v[208:211], v[98:101]
	v_mfma_f32_16x16x32_bf16 v[90:93], v[142:145], v[216:219], v[90:93]
	v_mfma_f32_16x16x32_bf16 v[82:85], v[160:163], v[216:219], v[82:85]
	v_mfma_f32_16x16x32_bf16 v[126:129], v[156:159], v[196:199], v[126:129]
	v_mfma_f32_16x16x32_bf16 v[122:125], v[164:167], v[196:199], v[122:125]
	v_mfma_f32_16x16x32_bf16 v[118:121], v[156:159], v[204:207], v[118:121]
	v_mfma_f32_16x16x32_bf16 v[114:117], v[164:167], v[204:207], v[114:117]
	v_mfma_f32_16x16x32_bf16 v[106:109], v[156:159], v[212:215], v[106:109]
	v_mfma_f32_16x16x32_bf16 v[98:101], v[164:167], v[212:215], v[98:101]
	v_mfma_f32_16x16x32_bf16 v[90:93], v[156:159], v[220:223], v[90:93]
	v_mfma_f32_16x16x32_bf16 v[82:85], v[164:167], v[220:223], v[82:85]
	s_setprio 0
	s_setprio 1
	v_mfma_f32_16x16x32_bf16 v[110:113], v[168:171], v[192:195], v[110:113]
	v_mfma_f32_16x16x32_bf16 v[102:105], v[176:179], v[192:195], v[102:105]
	v_mfma_f32_16x16x32_bf16 v[94:97], v[168:171], v[200:203], v[94:97]
	v_mfma_f32_16x16x32_bf16 v[86:89], v[176:179], v[200:203], v[86:89]
	v_mfma_f32_16x16x32_bf16 v[78:81], v[168:171], v[208:211], v[78:81]
	v_mfma_f32_16x16x32_bf16 v[74:77], v[176:179], v[208:211], v[74:77]
	v_mfma_f32_16x16x32_bf16 v[70:73], v[168:171], v[216:219], v[70:73]
	v_mfma_f32_16x16x32_bf16 v[66:69], v[176:179], v[216:219], v[66:69]
	v_mfma_f32_16x16x32_bf16 v[110:113], v[172:175], v[196:199], v[110:113]
	v_mfma_f32_16x16x32_bf16 v[102:105], v[188:191], v[196:199], v[102:105]
	v_mfma_f32_16x16x32_bf16 v[94:97], v[172:175], v[204:207], v[94:97]
	v_mfma_f32_16x16x32_bf16 v[86:89], v[188:191], v[204:207], v[86:89]
	v_mfma_f32_16x16x32_bf16 v[78:81], v[172:175], v[212:215], v[78:81]
	v_mfma_f32_16x16x32_bf16 v[74:77], v[188:191], v[212:215], v[74:77]
	v_mfma_f32_16x16x32_bf16 v[70:73], v[172:175], v[220:223], v[70:73]
	v_mfma_f32_16x16x32_bf16 v[66:69], v[188:191], v[220:223], v[66:69]
	s_setprio 0
	s_barrier
; #define PG8_STAGE(bufoff, gbase) do { _Pragma("unroll") for (int _i = 0; _i < 2; ++_i) \
;         __builtin_amdgcn_global_load_lds((const unsigned*)((const char*)(gbase) + voff[_i]), (LAS unsigned*)(lds + (bufoff) + ldsw + _i * 8192), 16, 0, 0); } while (0)
; #define PG8_LDA(dst, b, h) do { _Pragma("unroll") for (int m = 0; m < 4; ++m) _Pragma("unroll") for (int k = 0; k < 2; ++k) dst[m][k] = *(const LAS bf16x8*)(lds + PG8_SA(b, h) + aoff + m * 2048 + k * 1024); } while (0)
; #define PG8_MMA(ai, bj, At, Bt) do { __builtin_amdgcn_s_setprio(1); _Pragma("unroll") for (int m = 0; m < 4; ++m) _Pragma("unroll") for (int n = 0; n < 2; ++n) _Pragma("unroll") for (int k = 0; k < 2; ++k) \
;         acc[ai][bj][m][n] = __builtin_amdgcn_mfma_f32_16x16x32_bf16(Bt[n][k], At[m][k], acc[ai][bj][m][n], 0, 0, 0); __builtin_amdgcn_s_setprio(0); } while (0)
; #define PG8_WAIT_V(n) asm volatile("s_waitcnt vmcnt(" #n ")" ::: "memory")
; #define PG8_WAIT_L(n) asm volatile("s_waitcnt lgkmcnt(" #n ")" ::: "memory")
; #define PG8_BAR __builtin_amdgcn_s_barrier()
; #define PG8_SCHED __builtin_amdgcn_sched_barrier(0)
; template <int EPI> ...
;     ...
;             PG8_LDA(At, 1, 1); PG8_STAGE(PG8_SB(1, 0), b3); PG8_STAGE(PG8_SB(1, 1), b3 + hstep); PG8_STAGE(PG8_SA(1, 0), a3);
;             PG8_WAIT_V(8); PG8_WAIT_L(0); PG8_BAR; PG8_MMA(1, 0, At, B0); PG8_MMA(1, 1, At, B1); PG8_BAR; PG8_SCHED;
;         }
;         if (wr == 0) PG8_BAR;
;         if (SPLIT && cur_slice >= 0) {
	s_add_i32 s36, s58, s39
	v_lshl_add_u64 v[146:147], v[146:147], 0, s[10:11]
	s_mov_b32 m0, s36
	ds_read_b128 v[192:195], v154 offset:49152
	ds_read_b128 v[196:199], v154 offset:50176
	ds_read_b128 v[200:203], v154 offset:51200
	ds_read_b128 v[204:207], v154 offset:52224
	ds_read_b128 v[208:211], v154 offset:53248
	ds_read_b128 v[212:215], v154 offset:54272
	ds_read_b128 v[216:219], v154 offset:55296
	ds_read_b128 v[220:223], v154 offset:56320
	global_load_lds_dwordx4 v[146:147], off
	s_add_i32 m0, s36, 0x2000
	s_add_u32 s34, s34, 0x40080
	v_lshl_add_u64 v[146:147], v[180:181], 0, s[10:11]
	s_addc_u32 s35, s35, 0
	s_add_i32 s36, s59, s39
	global_load_lds_dwordx4 v[146:147], off
	v_lshl_add_u64 v[146:147], s[34:35], 0, v[130:131]
	s_mov_b32 m0, s36
	s_nop 0
	global_load_lds_dwordx4 v[146:147], off
	v_lshl_add_u64 v[146:147], s[34:35], 0, v[132:133]
	s_add_i32 m0, s36, 0x2000
	s_nop 0
	global_load_lds_dwordx4 v[146:147], off
	v_lshl_add_u64 v[146:147], v[224:225], 0, s[10:11]
	s_mov_b32 m0, s43
	s_nop 0
	global_load_lds_dwordx4 v[146:147], off
	v_lshl_add_u64 v[146:147], v[226:227], 0, s[10:11]
	s_mov_b32 m0, s44
	s_nop 0
	global_load_lds_dwordx4 v[146:147], off
	s_waitcnt vmcnt(8)
	s_waitcnt lgkmcnt(0)
	s_barrier
	s_setprio 1
	s_waitcnt lgkmcnt(0)
	v_mfma_f32_16x16x32_bf16 v[62:65], v[142:145], v[192:195], v[62:65]
	v_mfma_f32_16x16x32_bf16 v[58:61], v[160:163], v[192:195], v[58:61]
	v_mfma_f32_16x16x32_bf16 v[54:57], v[142:145], v[200:203], v[54:57]
	v_mfma_f32_16x16x32_bf16 v[50:53], v[160:163], v[200:203], v[50:53]
	v_mfma_f32_16x16x32_bf16 v[42:45], v[142:145], v[208:211], v[42:45]
	v_mfma_f32_16x16x32_bf16 v[34:37], v[160:163], v[208:211], v[34:37]
	v_mfma_f32_16x16x32_bf16 v[26:29], v[142:145], v[216:219], v[26:29]
	v_mfma_f32_16x16x32_bf16 v[18:21], v[160:163], v[216:219], v[18:21]
	v_mfma_f32_16x16x32_bf16 v[62:65], v[156:159], v[196:199], v[62:65]
	v_mfma_f32_16x16x32_bf16 v[58:61], v[164:167], v[196:199], v[58:61]
	v_mfma_f32_16x16x32_bf16 v[54:57], v[156:159], v[204:207], v[54:57]
	v_mfma_f32_16x16x32_bf16 v[50:53], v[164:167], v[204:207], v[50:53]
	v_mfma_f32_16x16x32_bf16 v[42:45], v[156:159], v[212:215], v[42:45]
	v_mfma_f32_16x16x32_bf16 v[34:37], v[164:167], v[212:215], v[34:37]
	v_mfma_f32_16x16x32_bf16 v[26:29], v[156:159], v[220:223], v[26:29]
	v_mfma_f32_16x16x32_bf16 v[18:21], v[164:167], v[220:223], v[18:21]
	s_setprio 0
	s_setprio 1
	v_mfma_f32_16x16x32_bf16 v[46:49], v[168:171], v[192:195], v[46:49]
	v_mfma_f32_16x16x32_bf16 v[38:41], v[176:179], v[192:195], v[38:41]
	v_mfma_f32_16x16x32_bf16 v[30:33], v[168:171], v[200:203], v[30:33]
	v_mfma_f32_16x16x32_bf16 v[22:25], v[176:179], v[200:203], v[22:25]
	v_mfma_f32_16x16x32_bf16 v[14:17], v[168:171], v[208:211], v[14:17]
	v_mfma_f32_16x16x32_bf16 v[10:13], v[176:179], v[208:211], v[10:13]
	v_mfma_f32_16x16x32_bf16 v[6:9], v[168:171], v[216:219], v[6:9]
	v_mfma_f32_16x16x32_bf16 v[2:5], v[176:179], v[216:219], v[2:5]
	v_mfma_f32_16x16x32_bf16 v[46:49], v[172:175], v[196:199], v[46:49]
	v_mfma_f32_16x16x32_bf16 v[38:41], v[188:191], v[196:199], v[38:41]
	v_mfma_f32_16x16x32_bf16 v[30:33], v[172:175], v[204:207], v[30:33]
	v_mfma_f32_16x16x32_bf16 v[22:25], v[188:191], v[204:207], v[22:25]
	v_mfma_f32_16x16x32_bf16 v[14:17], v[172:175], v[212:215], v[14:17]
	v_mfma_f32_16x16x32_bf16 v[10:13], v[188:191], v[212:215], v[10:13]
	v_mfma_f32_16x16x32_bf16 v[6:9], v[172:175], v[220:223], v[6:9]
	v_mfma_f32_16x16x32_bf16 v[2:5], v[188:191], v[220:223], v[2:5]
	s_setprio 0
	s_barrier
	s_add_u32 s30, s30, 0x100
	s_addc_u32 s31, s31, 0
	s_add_u32 s55, s55, 0x100
	s_addc_u32 s56, s56, 0
	s_cmp_ge_u32 s57, s52
	s_mov_b32 s34, s57
	s_cbranch_scc0 .LBB0_825
	s_mov_b32 s99, 1
	s_and_b64 vcc, exec, s[12:13]
	s_cbranch_vccz .LBB0_830
	s_barrier
	s_cmp_lt_i32 s0, 0
	s_mov_b64 s[30:31], -1
	s_cbranch_scc1 .LBB0_831

;     __device__ __forceinline__ bool next(int i, int& pm, int& pn, int& k0, int& nk, int& slice, int& src) const {
;     ...
;         if (nsplit == 0) return false;
;         int sidx = (int)(L - nwg);
;         if (sidx >= nslice_items) return false;
;         int ncol = nN;
;         if (glu && sidx >= 64) { sidx -= 64; src = 1; ncol = 4; }
;         const int tl = sidx / nsplit; slice = sidx - tl * nsplit; pm = 64 + tl / ncol; pn = tl % ncol; nk = nt / nsplit; k0 = slice * nk; return true;
.LBB0_1216:
	s_or_b64 exec, exec, s[2:3]
	v_readlane_b32 s0, v244, 62
	v_readlane_b32 s1, v244, 63
	s_waitcnt lgkmcnt(0)
	s_barrier
	s_mov_b32 s99, 0
	s_and_b64 vcc, exec, s[0:1]
	v_readfirstlane_b32 s12, v0
	s_cbranch_vccz .LBB0_1219
	v_readlane_b32 s6, v244, 33
	s_cmpk_lt_u32 s6, 0x158
	s_mov_b64 s[10:11], 0
	s_cbranch_scc0 .LBB0_1220
	s_and_b32 s2, s6, 0xff
	s_mulk_i32 s2, 0x75
	s_lshr_b32 s2, s2, 8
	s_add_i32 s3, s6, 0xffffff00
	s_sub_i32 s6, s6, s2
	s_bfe_u32 s6, s6, 0x70001
	s_add_i32 s6, s6, s2
	s_bfe_u32 s2, s6, 0x50003
	s_mul_i32 s2, s2, -11
	s_add_i32 s2, s2, s3
	s_cmp_gt_u32 s3, 43
	s_cselect_b32 s35, 0x41, 64
	s_bfe_u32 s36, s6, 0x20003
	s_lshl_b32 s6, s2, 2
	s_ashr_i32 s7, s6, 31
	s_lshl_b64 s[6:7], s[6:7], 7
	s_mov_b64 s[8:9], -1
	s_mov_b32 s53, 4
	s_and_b64 vcc, exec, s[10:11]
	s_cbranch_vccnz .LBB0_1221
	s_branch .LBB0_1226

; #define PG8_STAGE(bufoff, gbase) do { _Pragma("unroll") for (int _i = 0; _i < 2; ++_i) \
;         __builtin_amdgcn_global_load_lds((const unsigned*)((const char*)(gbase) + voff[_i]), (LAS unsigned*)(lds + (bufoff) + ldsw + _i * 8192), 16, 0, 0); } while (0)
; #define PG8_LDA(dst, b, h) do { _Pragma("unroll") for (int m = 0; m < 4; ++m) _Pragma("unroll") for (int k = 0; k < 2; ++k) dst[m][k] = *(const LAS bf16x8*)(lds + PG8_SA(b, h) + aoff + m * 2048 + k * 1024); } while (0)
; #define PG8_LDB(dst, b, h) do { _Pragma("unroll") for (int n = 0; n < 2; ++n) _Pragma("unroll") for (int k = 0; k < 2; ++k) dst[n][k] = *(const LAS bf16x8*)(lds + PG8_SB(b, h) + boff + n * 2048 + k * 1024); } while (0)
; #define PG8_MMA(ai, bj, At, Bt) do { __builtin_amdgcn_s_setprio(1); _Pragma("unroll") for (int m = 0; m < 4; ++m) _Pragma("unroll") for (int n = 0; n < 2; ++n) _Pragma("unroll") for (int k = 0; k < 2; ++k) \
;         acc[ai][bj][m][n] = __builtin_amdgcn_mfma_f32_16x16x32_bf16(Bt[n][k], At[m][k], acc[ai][bj][m][n], 0, 0, 0); __builtin_amdgcn_s_setprio(0); } while (0)
; #define PG8_WAIT_V(n) asm volatile("s_waitcnt vmcnt(" #n ")" ::: "memory")
; #define PG8_WAIT_L(n) asm volatile("s_waitcnt lgkmcnt(" #n ")" ::: "memory")
; #define PG8_BAR __builtin_amdgcn_s_barrier()
; #define PG8_SCHED __builtin_amdgcn_sched_barrier(0)
; template <int EPI> ...
;     ...
;         for (int t = 0; t < cnk; t += 2) {
;             const bool last = (t == cnk - 2);
;             const char* a1 = cA + (size_t)(t + 1) * kstep;
;             const char* a2 = last ? nA : cA + (size_t)(t + 2) * kstep; const char* b2 = last ? nB : cB + (size_t)(t + 2) * kstep;
;             const char* a3 = a2 + kstep; const char* b3 = b2 + kstep;
;             PG8_LDB(B0, 0, 0); PG8_LDB(B1, 0, 1); PG8_SCHED; PG8_LDA(At, 0, 0); PG8_STAGE(PG8_SA(1, 1), a1 + hstep);
;             PG8_WAIT_V(8); PG8_WAIT_L(0); PG8_BAR; PG8_MMA(0, 0, At, B0); PG8_MMA(0, 1, At, B1); PG8_BAR; PG8_SCHED;
;     ...
;         for (int a = 0; a < 2; ++a)
; #pragma unroll
;             for (int b = 0; b < 2; ++b)
; #pragma unroll
;                 for (int m = 0; m < 4; ++m)
; #pragma unroll
;                     for (int n = 0; n < 2; ++n) acc[a][b][m][n] = (f32x4){0.f, 0.f, 0.f, 0.f};
;         cur_pm = nxt_pm; cur_pn = nxt_pn; cur_k0 = nxt_k0; cur_nk = nxt_nk; cur_slice = nxt_slice; cur_src = nxt_src; cA = nA; cB = nB; ++ui;
.LBB0_1245:
	s_add_i32 s54, s53, -2
	s_add_u32 s55, s26, 0x100
	v_mov_b32_e32 v0, 0
	s_addc_u32 s56, s27, 0
	s_mov_b32 s28, 0
	v_mov_b32_e32 v1, v0
	v_mov_b32_e32 v2, v0
	v_mov_b32_e32 v3, v0
	v_mov_b32_e32 v4, v0
	v_mov_b32_e32 v5, v0
	v_mov_b32_e32 v6, v0
	v_mov_b32_e32 v7, v0
	v_mov_b32_e32 v8, v0
	v_mov_b32_e32 v9, v0
	v_mov_b32_e32 v10, v0
	v_mov_b32_e32 v11, v0
	v_mov_b32_e32 v12, v0
	v_mov_b32_e32 v13, v0
	v_mov_b32_e32 v14, v0
	v_mov_b32_e32 v15, v0
	v_mov_b32_e32 v20, v0
	v_mov_b32_e32 v21, v0
	v_mov_b32_e32 v22, v0
	v_mov_b32_e32 v23, v0
	v_mov_b32_e32 v28, v0
	v_mov_b32_e32 v29, v0
	v_mov_b32_e32 v30, v0
	v_mov_b32_e32 v31, v0
	v_mov_b32_e32 v36, v0
	v_mov_b32_e32 v37, v0
	v_mov_b32_e32 v38, v0
	v_mov_b32_e32 v39, v0
	v_mov_b32_e32 v44, v0
	v_mov_b32_e32 v45, v0
	v_mov_b32_e32 v46, v0
	v_mov_b32_e32 v47, v0
	v_mov_b32_e32 v16, v0
	v_mov_b32_e32 v17, v0
	v_mov_b32_e32 v18, v0
	v_mov_b32_e32 v19, v0
	v_mov_b32_e32 v24, v0
	v_mov_b32_e32 v25, v0
	v_mov_b32_e32 v26, v0
	v_mov_b32_e32 v27, v0
	v_mov_b32_e32 v32, v0
	v_mov_b32_e32 v33, v0
	v_mov_b32_e32 v34, v0
	v_mov_b32_e32 v35, v0
	v_mov_b32_e32 v40, v0
	v_mov_b32_e32 v41, v0
	v_mov_b32_e32 v42, v0
	v_mov_b32_e32 v43, v0
	v_mov_b32_e32 v48, v0
	v_mov_b32_e32 v49, v0
	v_mov_b32_e32 v50, v0
	v_mov_b32_e32 v51, v0
	v_mov_b32_e32 v52, v0
	v_mov_b32_e32 v53, v0
	v_mov_b32_e32 v54, v0
	v_mov_b32_e32 v55, v0
	v_mov_b32_e32 v56, v0
	v_mov_b32_e32 v57, v0
	v_mov_b32_e32 v58, v0
	v_mov_b32_e32 v59, v0
	v_mov_b32_e32 v60, v0
	v_mov_b32_e32 v61, v0
	v_mov_b32_e32 v62, v0
	v_mov_b32_e32 v63, v0
	v_mov_b32_e32 v64, v0
	v_mov_b32_e32 v65, v0
	v_mov_b32_e32 v66, v0
	v_mov_b32_e32 v67, v0
	v_mov_b32_e32 v68, v0
	v_mov_b32_e32 v69, v0
	v_mov_b32_e32 v70, v0
	v_mov_b32_e32 v71, v0
	v_mov_b32_e32 v72, v0
	v_mov_b32_e32 v73, v0
	v_mov_b32_e32 v74, v0
	v_mov_b32_e32 v75, v0
	v_mov_b32_e32 v76, v0
	v_mov_b32_e32 v77, v0
	v_mov_b32_e32 v78, v0
	v_mov_b32_e32 v79, v0
	v_mov_b32_e32 v84, v0
	v_mov_b32_e32 v85, v0
	v_mov_b32_e32 v86, v0
	v_mov_b32_e32 v87, v0
	v_mov_b32_e32 v92, v0
	v_mov_b32_e32 v93, v0
	v_mov_b32_e32 v94, v0
	v_mov_b32_e32 v95, v0
	v_mov_b32_e32 v100, v0
	v_mov_b32_e32 v101, v0
	v_mov_b32_e32 v102, v0
	v_mov_b32_e32 v103, v0
	v_mov_b32_e32 v108, v0
	v_mov_b32_e32 v109, v0
	v_mov_b32_e32 v110, v0
	v_mov_b32_e32 v111, v0
	v_mov_b32_e32 v80, v0
	v_mov_b32_e32 v81, v0
	v_mov_b32_e32 v82, v0
	v_mov_b32_e32 v83, v0
	v_mov_b32_e32 v88, v0
	v_mov_b32_e32 v89, v0
	v_mov_b32_e32 v90, v0
	v_mov_b32_e32 v91, v0
	v_mov_b32_e32 v96, v0
	v_mov_b32_e32 v97, v0
	v_mov_b32_e32 v98, v0
	v_mov_b32_e32 v99, v0
	v_mov_b32_e32 v104, v0
	v_mov_b32_e32 v105, v0
	v_mov_b32_e32 v106, v0
	v_mov_b32_e32 v107, v0
	v_mov_b32_e32 v112, v0
	v_mov_b32_e32 v113, v0
	v_mov_b32_e32 v114, v0
	v_mov_b32_e32 v115, v0
	v_mov_b32_e32 v116, v0
	v_mov_b32_e32 v117, v0
	v_mov_b32_e32 v118, v0
	v_mov_b32_e32 v119, v0
	v_mov_b32_e32 v120, v0
	v_mov_b32_e32 v121, v0
	v_mov_b32_e32 v122, v0
	v_mov_b32_e32 v123, v0
	v_mov_b32_e32 v124, v0
	v_mov_b32_e32 v125, v0
	v_mov_b32_e32 v126, v0
	v_mov_b32_e32 v127, v0
.LBB0_1246:
	ds_read_b128 v[128:131], v156
	ds_read_b128 v[132:135], v156 offset:1024
	ds_read_b128 v[148:151], v156 offset:2048
	ds_read_b128 v[160:163], v156 offset:3072
	ds_read_b128 v[164:167], v157
	ds_read_b128 v[168:171], v157 offset:1024
	ds_read_b128 v[172:175], v157 offset:2048
	ds_read_b128 v[176:179], v157 offset:3072
	s_add_i32 s57, s28, 2
	s_add_u32 s26, s24, 0x100
	s_addc_u32 s27, s25, 0
	s_cmp_eq_u32 s54, s28
	s_cselect_b32 s28, s18, s55
	s_cselect_b32 s31, s17, s27
	s_cselect_b32 s30, s16, s26
	s_cselect_b32 s29, s19, s56
	v_lshl_add_u64 v[180:181], s[24:25], 0, v[142:143]
	s_add_i32 m0, s38, 0xc000
	ds_read_b128 v[194:197], v158
	ds_read_b128 v[198:201], v158 offset:1024
	ds_read_b128 v[202:205], v158 offset:2048
	ds_read_b128 v[206:209], v158 offset:3072
	ds_read_b128 v[210:213], v158 offset:4096
	ds_read_b128 v[214:217], v158 offset:5120
	ds_read_b128 v[218:221], v158 offset:6144
	ds_read_b128 v[222:225], v158 offset:7168
	global_load_lds_dwordx4 v[180:181], off
	v_lshl_add_u64 v[180:181], s[24:25], 0, v[144:145]
	s_add_i32 m0, s38, 0xe000
	s_nop 0
	global_load_lds_dwordx4 v[180:181], off
	s_cmp_eq_u32 s99, 0
	s_cbranch_scc1 .Lrx_DOWN_s0
	s_waitcnt vmcnt(40)
	s_branch .Lrx_DOWN_d0

; #define PG8_STAGE(bufoff, gbase) do { _Pragma("unroll") for (int _i = 0; _i < 2; ++_i) \
;         __builtin_amdgcn_global_load_lds((const unsigned*)((const char*)(gbase) + voff[_i]), (LAS unsigned*)(lds + (bufoff) + ldsw + _i * 8192), 16, 0, 0); } while (0)
; #define PG8_LDA(dst, b, h) do { _Pragma("unroll") for (int m = 0; m < 4; ++m) _Pragma("unroll") for (int k = 0; k < 2; ++k) dst[m][k] = *(const LAS bf16x8*)(lds + PG8_SA(b, h) + aoff + m * 2048 + k * 1024); } while (0)
; #define PG8_MMA(ai, bj, At, Bt) do { __builtin_amdgcn_s_setprio(1); _Pragma("unroll") for (int m = 0; m < 4; ++m) _Pragma("unroll") for (int n = 0; n < 2; ++n) _Pragma("unroll") for (int k = 0; k < 2; ++k) \
;         acc[ai][bj][m][n] = __builtin_amdgcn_mfma_f32_16x16x32_bf16(Bt[n][k], At[m][k], acc[ai][bj][m][n], 0, 0, 0); __builtin_amdgcn_s_setprio(0); } while (0)
; #define PG8_WAIT_V(n) asm volatile("s_waitcnt vmcnt(" #n ")" ::: "memory")
; #define PG8_WAIT_L(n) asm volatile("s_waitcnt lgkmcnt(" #n ")" ::: "memory")
; #define PG8_BAR __builtin_amdgcn_s_barrier()
; #define PG8_SCHED __builtin_amdgcn_sched_barrier(0)
; template <int EPI> ...
;     ...
;             PG8_WAIT_V(8); PG8_WAIT_L(0); PG8_BAR; PG8_MMA(0, 0, At, B0); PG8_MMA(0, 1, At, B1); PG8_BAR; PG8_SCHED;
;             PG8_LDA(At, 0, 1); PG8_STAGE(PG8_SB(0, 0), b2); PG8_STAGE(PG8_SB(0, 1), b2 + hstep); PG8_STAGE(PG8_SA(0, 0), a2);
.Lrx_DOWN_d0:
	s_waitcnt lgkmcnt(0)
	s_barrier
	s_setprio 1
	s_waitcnt lgkmcnt(0)
	v_mfma_f32_16x16x32_bf16 v[124:127], v[128:131], v[194:197], v[124:127]
	v_mfma_f32_16x16x32_bf16 v[120:123], v[148:151], v[194:197], v[120:123]
	v_mfma_f32_16x16x32_bf16 v[116:119], v[128:131], v[202:205], v[116:119]
	v_mfma_f32_16x16x32_bf16 v[112:115], v[148:151], v[202:205], v[112:115]
	v_mfma_f32_16x16x32_bf16 v[104:107], v[128:131], v[210:213], v[104:107]
	v_mfma_f32_16x16x32_bf16 v[96:99], v[148:151], v[210:213], v[96:99]
	v_mfma_f32_16x16x32_bf16 v[88:91], v[128:131], v[218:221], v[88:91]
	v_mfma_f32_16x16x32_bf16 v[80:83], v[148:151], v[218:221], v[80:83]
	v_mfma_f32_16x16x32_bf16 v[124:127], v[132:135], v[198:201], v[124:127]
	v_mfma_f32_16x16x32_bf16 v[120:123], v[160:163], v[198:201], v[120:123]
	v_mfma_f32_16x16x32_bf16 v[116:119], v[132:135], v[206:209], v[116:119]
	v_mfma_f32_16x16x32_bf16 v[112:115], v[160:163], v[206:209], v[112:115]
	v_mfma_f32_16x16x32_bf16 v[104:107], v[132:135], v[214:217], v[104:107]
	v_mfma_f32_16x16x32_bf16 v[96:99], v[160:163], v[214:217], v[96:99]
	v_mfma_f32_16x16x32_bf16 v[88:91], v[132:135], v[222:225], v[88:91]
	v_mfma_f32_16x16x32_bf16 v[80:83], v[160:163], v[222:225], v[80:83]
	s_setprio 0
	s_setprio 1
	v_mfma_f32_16x16x32_bf16 v[108:111], v[164:167], v[194:197], v[108:111]
	v_mfma_f32_16x16x32_bf16 v[100:103], v[172:175], v[194:197], v[100:103]
	v_mfma_f32_16x16x32_bf16 v[92:95], v[164:167], v[202:205], v[92:95]
	v_mfma_f32_16x16x32_bf16 v[84:87], v[172:175], v[202:205], v[84:87]
	v_mfma_f32_16x16x32_bf16 v[76:79], v[164:167], v[210:213], v[76:79]
	v_mfma_f32_16x16x32_bf16 v[72:75], v[172:175], v[210:213], v[72:75]
	v_mfma_f32_16x16x32_bf16 v[68:71], v[164:167], v[218:221], v[68:71]
	v_mfma_f32_16x16x32_bf16 v[64:67], v[172:175], v[218:221], v[64:67]
	v_mfma_f32_16x16x32_bf16 v[108:111], v[168:171], v[198:201], v[108:111]
	v_mfma_f32_16x16x32_bf16 v[100:103], v[176:179], v[198:201], v[100:103]
	v_mfma_f32_16x16x32_bf16 v[92:95], v[168:171], v[206:209], v[92:95]
	v_mfma_f32_16x16x32_bf16 v[84:87], v[176:179], v[206:209], v[84:87]
	v_mfma_f32_16x16x32_bf16 v[76:79], v[168:171], v[214:217], v[76:79]
	v_mfma_f32_16x16x32_bf16 v[72:75], v[176:179], v[214:217], v[72:75]
	v_mfma_f32_16x16x32_bf16 v[68:71], v[168:171], v[222:225], v[68:71]
	v_mfma_f32_16x16x32_bf16 v[64:67], v[176:179], v[222:225], v[64:67]
	s_setprio 0
	s_barrier
	s_add_i32 s24, s45, s37
	v_lshl_add_u64 v[180:181], s[28:29], 0, v[136:137]
	s_mov_b32 m0, s24
	ds_read_b128 v[194:197], v158 offset:16384
	ds_read_b128 v[198:201], v158 offset:17408
	ds_read_b128 v[202:205], v158 offset:18432
	ds_read_b128 v[206:209], v158 offset:19456
	ds_read_b128 v[210:213], v158 offset:20480
	ds_read_b128 v[214:217], v158 offset:21504
	ds_read_b128 v[218:221], v158 offset:22528
	ds_read_b128 v[222:225], v158 offset:23552
	global_load_lds_dwordx4 v[180:181], off
	s_add_i32 m0, s24, 0x2000
	s_add_u32 s24, s28, 0xb0000
	v_lshl_add_u64 v[186:187], s[28:29], 0, v[138:139]
	s_addc_u32 s25, s29, 0
	s_add_i32 s58, s46, s37
	global_load_lds_dwordx4 v[186:187], off
	v_lshl_add_u64 v[226:227], s[24:25], 0, v[136:137]
	s_mov_b32 m0, s58
	v_lshl_add_u64 v[228:229], s[30:31], 0, v[138:139]
	global_load_lds_dwordx4 v[226:227], off
	v_lshl_add_u64 v[226:227], s[24:25], 0, v[138:139]
	s_add_i32 m0, s58, 0x2000
	s_nop 0
	global_load_lds_dwordx4 v[226:227], off
	v_lshl_add_u64 v[226:227], s[30:31], 0, v[136:137]
	s_mov_b32 m0, s38
	s_nop 0
	global_load_lds_dwordx4 v[226:227], off
	s_mov_b32 m0, s39
	s_nop 0
	global_load_lds_dwordx4 v[228:229], off
	s_cmp_eq_u32 s99, 0
	s_cbranch_scc1 .Lrx_DOWN_s1
	s_waitcnt vmcnt(40)
	s_branch .Lrx_DOWN_d1

; #define PG8_STAGE(bufoff, gbase) do { _Pragma("unroll") for (int _i = 0; _i < 2; ++_i) \
;         __builtin_amdgcn_global_load_lds((const unsigned*)((const char*)(gbase) + voff[_i]), (LAS unsigned*)(lds + (bufoff) + ldsw + _i * 8192), 16, 0, 0); } while (0)
; #define PG8_LDA(dst, b, h) do { _Pragma("unroll") for (int m = 0; m < 4; ++m) _Pragma("unroll") for (int k = 0; k < 2; ++k) dst[m][k] = *(const LAS bf16x8*)(lds + PG8_SA(b, h) + aoff + m * 2048 + k * 1024); } while (0)
; #define PG8_LDB(dst, b, h) do { _Pragma("unroll") for (int n = 0; n < 2; ++n) _Pragma("unroll") for (int k = 0; k < 2; ++k) dst[n][k] = *(const LAS bf16x8*)(lds + PG8_SB(b, h) + boff + n * 2048 + k * 1024); } while (0)
; #define PG8_MMA(ai, bj, At, Bt) do { __builtin_amdgcn_s_setprio(1); _Pragma("unroll") for (int m = 0; m < 4; ++m) _Pragma("unroll") for (int n = 0; n < 2; ++n) _Pragma("unroll") for (int k = 0; k < 2; ++k) \
;         acc[ai][bj][m][n] = __builtin_amdgcn_mfma_f32_16x16x32_bf16(Bt[n][k], At[m][k], acc[ai][bj][m][n], 0, 0, 0); __builtin_amdgcn_s_setprio(0); } while (0)
; #define PG8_WAIT_V(n) asm volatile("s_waitcnt vmcnt(" #n ")" ::: "memory")
; #define PG8_WAIT_L(n) asm volatile("s_waitcnt lgkmcnt(" #n ")" ::: "memory")
; #define PG8_BAR __builtin_amdgcn_s_barrier()
; #define PG8_SCHED __builtin_amdgcn_sched_barrier(0)
; template <int EPI> ...
;     ...
;             PG8_LDA(At, 0, 1); PG8_STAGE(PG8_SB(0, 0), b2); PG8_STAGE(PG8_SB(0, 1), b2 + hstep); PG8_STAGE(PG8_SA(0, 0), a2);
;             PG8_WAIT_V(8); PG8_WAIT_L(0); PG8_BAR; PG8_MMA(1, 0, At, B0); PG8_MMA(1, 1, At, B1); PG8_BAR; PG8_SCHED;
;             PG8_LDB(B0, 1, 0); PG8_LDB(B1, 1, 1); PG8_SCHED; PG8_LDA(At, 1, 0); PG8_STAGE(PG8_SA(0, 1), a2 + hstep);
;             PG8_WAIT_V(8); PG8_WAIT_L(0); PG8_BAR; PG8_MMA(0, 0, At, B0); PG8_MMA(0, 1, At, B1); PG8_BAR; PG8_SCHED;
.Lrx_DOWN_d1:
	s_mov_b32 s99, 0
	s_waitcnt lgkmcnt(0)
	s_barrier
	s_setprio 1
	s_waitcnt lgkmcnt(0)
	v_mfma_f32_16x16x32_bf16 v[60:63], v[128:131], v[194:197], v[60:63]
	v_mfma_f32_16x16x32_bf16 v[56:59], v[148:151], v[194:197], v[56:59]
	v_mfma_f32_16x16x32_bf16 v[52:55], v[128:131], v[202:205], v[52:55]
	v_mfma_f32_16x16x32_bf16 v[48:51], v[148:151], v[202:205], v[48:51]
	v_mfma_f32_16x16x32_bf16 v[40:43], v[128:131], v[210:213], v[40:43]
	v_mfma_f32_16x16x32_bf16 v[32:35], v[148:151], v[210:213], v[32:35]
	v_mfma_f32_16x16x32_bf16 v[24:27], v[128:131], v[218:221], v[24:27]
	v_mfma_f32_16x16x32_bf16 v[16:19], v[148:151], v[218:221], v[16:19]
	v_mfma_f32_16x16x32_bf16 v[60:63], v[132:135], v[198:201], v[60:63]
	v_mfma_f32_16x16x32_bf16 v[56:59], v[160:163], v[198:201], v[56:59]
	v_mfma_f32_16x16x32_bf16 v[52:55], v[132:135], v[206:209], v[52:55]
	v_mfma_f32_16x16x32_bf16 v[48:51], v[160:163], v[206:209], v[48:51]
	v_mfma_f32_16x16x32_bf16 v[40:43], v[132:135], v[214:217], v[40:43]
	v_mfma_f32_16x16x32_bf16 v[32:35], v[160:163], v[214:217], v[32:35]
	v_mfma_f32_16x16x32_bf16 v[24:27], v[132:135], v[222:225], v[24:27]
	v_mfma_f32_16x16x32_bf16 v[16:19], v[160:163], v[222:225], v[16:19]
	s_setprio 0
	s_setprio 1
	v_mfma_f32_16x16x32_bf16 v[44:47], v[164:167], v[194:197], v[44:47]
	v_mfma_f32_16x16x32_bf16 v[36:39], v[172:175], v[194:197], v[36:39]
	v_mfma_f32_16x16x32_bf16 v[28:31], v[164:167], v[202:205], v[28:31]
	v_mfma_f32_16x16x32_bf16 v[20:23], v[172:175], v[202:205], v[20:23]
	v_mfma_f32_16x16x32_bf16 v[12:15], v[164:167], v[210:213], v[12:15]
	v_mfma_f32_16x16x32_bf16 v[8:11], v[172:175], v[210:213], v[8:11]
	v_mfma_f32_16x16x32_bf16 v[4:7], v[164:167], v[218:221], v[4:7]
	v_mfma_f32_16x16x32_bf16 v[0:3], v[172:175], v[218:221], v[0:3]
	v_mfma_f32_16x16x32_bf16 v[44:47], v[168:171], v[198:201], v[44:47]
	v_mfma_f32_16x16x32_bf16 v[36:39], v[176:179], v[198:201], v[36:39]
	v_mfma_f32_16x16x32_bf16 v[28:31], v[168:171], v[206:209], v[28:31]
	v_mfma_f32_16x16x32_bf16 v[20:23], v[176:179], v[206:209], v[20:23]
	v_mfma_f32_16x16x32_bf16 v[12:15], v[168:171], v[214:217], v[12:15]
	v_mfma_f32_16x16x32_bf16 v[8:11], v[176:179], v[214:217], v[8:11]
	v_mfma_f32_16x16x32_bf16 v[4:7], v[168:171], v[222:225], v[4:7]
	v_mfma_f32_16x16x32_bf16 v[0:3], v[176:179], v[222:225], v[0:3]
	s_setprio 0
	s_barrier
	s_add_i32 s58, 0, 0x18000
	v_add_u32_e32 v159, s58, v153
	s_add_i32 s59, 0, 0x1c000
	ds_read_b128 v[128:131], v159
	ds_read_b128 v[132:135], v159 offset:1024
	ds_read_b128 v[148:151], v159 offset:2048
	ds_read_b128 v[160:163], v159 offset:3072
	v_add_u32_e32 v159, s59, v153
	ds_read_b128 v[164:167], v159
	ds_read_b128 v[168:171], v159 offset:1024
	ds_read_b128 v[172:175], v159 offset:2048
	ds_read_b128 v[176:179], v159 offset:3072
	s_add_u32 s24, s30, 0xb0000
	s_addc_u32 s25, s31, 0
	s_mov_b32 m0, s40
	v_lshl_add_u64 v[230:231], s[24:25], 0, v[136:137]
	ds_read_b128 v[194:197], v158 offset:32768
	ds_read_b128 v[198:201], v158 offset:33792
	ds_read_b128 v[202:205], v158 offset:34816
	ds_read_b128 v[206:209], v158 offset:35840
	ds_read_b128 v[210:213], v158 offset:36864
	ds_read_b128 v[214:217], v158 offset:37888
	ds_read_b128 v[218:221], v158 offset:38912
	ds_read_b128 v[222:225], v158 offset:39936
	global_load_lds_dwordx4 v[230:231], off
	v_lshl_add_u64 v[230:231], s[24:25], 0, v[138:139]
	s_mov_b32 m0, s41
	s_nop 0
	global_load_lds_dwordx4 v[230:231], off
	s_waitcnt vmcnt(8)
	s_waitcnt lgkmcnt(0)
	s_barrier
	s_setprio 1
	s_waitcnt lgkmcnt(0)
	v_mfma_f32_16x16x32_bf16 v[124:127], v[128:131], v[194:197], v[124:127]
	v_mfma_f32_16x16x32_bf16 v[120:123], v[148:151], v[194:197], v[120:123]
	v_mfma_f32_16x16x32_bf16 v[116:119], v[128:131], v[202:205], v[116:119]
	v_mfma_f32_16x16x32_bf16 v[112:115], v[148:151], v[202:205], v[112:115]
	v_mfma_f32_16x16x32_bf16 v[104:107], v[128:131], v[210:213], v[104:107]
	v_mfma_f32_16x16x32_bf16 v[96:99], v[148:151], v[210:213], v[96:99]
	v_mfma_f32_16x16x32_bf16 v[88:91], v[128:131], v[218:221], v[88:91]
	v_mfma_f32_16x16x32_bf16 v[80:83], v[148:151], v[218:221], v[80:83]
	v_mfma_f32_16x16x32_bf16 v[124:127], v[132:135], v[198:201], v[124:127]
	v_mfma_f32_16x16x32_bf16 v[120:123], v[160:163], v[198:201], v[120:123]
	v_mfma_f32_16x16x32_bf16 v[116:119], v[132:135], v[206:209], v[116:119]
	v_mfma_f32_16x16x32_bf16 v[112:115], v[160:163], v[206:209], v[112:115]
	v_mfma_f32_16x16x32_bf16 v[104:107], v[132:135], v[214:217], v[104:107]
	v_mfma_f32_16x16x32_bf16 v[96:99], v[160:163], v[214:217], v[96:99]
	v_mfma_f32_16x16x32_bf16 v[88:91], v[132:135], v[222:225], v[88:91]
	v_mfma_f32_16x16x32_bf16 v[80:83], v[160:163], v[222:225], v[80:83]
	s_setprio 0
	s_setprio 1
	v_mfma_f32_16x16x32_bf16 v[108:111], v[164:167], v[194:197], v[108:111]
	v_mfma_f32_16x16x32_bf16 v[100:103], v[172:175], v[194:197], v[100:103]
	v_mfma_f32_16x16x32_bf16 v[92:95], v[164:167], v[202:205], v[92:95]
	v_mfma_f32_16x16x32_bf16 v[84:87], v[172:175], v[202:205], v[84:87]
	v_mfma_f32_16x16x32_bf16 v[76:79], v[164:167], v[210:213], v[76:79]
	v_mfma_f32_16x16x32_bf16 v[72:75], v[172:175], v[210:213], v[72:75]
	v_mfma_f32_16x16x32_bf16 v[68:71], v[164:167], v[218:221], v[68:71]
	v_mfma_f32_16x16x32_bf16 v[64:67], v[172:175], v[218:221], v[64:67]
	v_mfma_f32_16x16x32_bf16 v[108:111], v[168:171], v[198:201], v[108:111]
	v_mfma_f32_16x16x32_bf16 v[100:103], v[176:179], v[198:201], v[100:103]
	v_mfma_f32_16x16x32_bf16 v[92:95], v[168:171], v[206:209], v[92:95]
	v_mfma_f32_16x16x32_bf16 v[84:87], v[176:179], v[206:209], v[84:87]
	v_mfma_f32_16x16x32_bf16 v[76:79], v[168:171], v[214:217], v[76:79]
	v_mfma_f32_16x16x32_bf16 v[72:75], v[176:179], v[214:217], v[72:75]
	v_mfma_f32_16x16x32_bf16 v[68:71], v[168:171], v[222:225], v[68:71]
	v_mfma_f32_16x16x32_bf16 v[64:67], v[176:179], v[222:225], v[64:67]
	s_setprio 0
	s_barrier
; #define PG8_STAGE(bufoff, gbase) do { _Pragma("unroll") for (int _i = 0; _i < 2; ++_i) \
;         __builtin_amdgcn_global_load_lds((const unsigned*)((const char*)(gbase) + voff[_i]), (LAS unsigned*)(lds + (bufoff) + ldsw + _i * 8192), 16, 0, 0); } while (0)
; #define PG8_LDA(dst, b, h) do { _Pragma("unroll") for (int m = 0; m < 4; ++m) _Pragma("unroll") for (int k = 0; k < 2; ++k) dst[m][k] = *(const LAS bf16x8*)(lds + PG8_SA(b, h) + aoff + m * 2048 + k * 1024); } while (0)
; #define PG8_MMA(ai, bj, At, Bt) do { __builtin_amdgcn_s_setprio(1); _Pragma("unroll") for (int m = 0; m < 4; ++m) _Pragma("unroll") for (int n = 0; n < 2; ++n) _Pragma("unroll") for (int k = 0; k < 2; ++k) \
;         acc[ai][bj][m][n] = __builtin_amdgcn_mfma_f32_16x16x32_bf16(Bt[n][k], At[m][k], acc[ai][bj][m][n], 0, 0, 0); __builtin_amdgcn_s_setprio(0); } while (0)
; #define PG8_WAIT_V(n) asm volatile("s_waitcnt vmcnt(" #n ")" ::: "memory")
; #define PG8_WAIT_L(n) asm volatile("s_waitcnt lgkmcnt(" #n ")" ::: "memory")
; #define PG8_BAR __builtin_amdgcn_s_barrier()
; #define PG8_SCHED __builtin_amdgcn_sched_barrier(0)
; template <int EPI> ...
;     ...
;             PG8_LDA(At, 1, 1); PG8_STAGE(PG8_SB(1, 0), b3); PG8_STAGE(PG8_SB(1, 1), b3 + hstep); PG8_STAGE(PG8_SA(1, 0), a3);
;             PG8_WAIT_V(8); PG8_WAIT_L(0); PG8_BAR; PG8_MMA(1, 0, At, B0); PG8_MMA(1, 1, At, B1); PG8_BAR; PG8_SCHED;
;         }
;         if (wr == 0) PG8_BAR;
;         if (SPLIT && cur_slice >= 0) {
	s_add_i32 s24, s58, s37
	v_lshl_add_u64 v[180:181], v[180:181], 0, s[10:11]
	s_mov_b32 m0, s24
	ds_read_b128 v[194:197], v158 offset:49152
	ds_read_b128 v[198:201], v158 offset:50176
	ds_read_b128 v[202:205], v158 offset:51200
	ds_read_b128 v[206:209], v158 offset:52224
	ds_read_b128 v[210:213], v158 offset:53248
	ds_read_b128 v[214:217], v158 offset:54272
	ds_read_b128 v[218:221], v158 offset:55296
	ds_read_b128 v[222:225], v158 offset:56320
	global_load_lds_dwordx4 v[180:181], off
	s_add_i32 m0, s24, 0x2000
	s_add_u32 s24, s28, 0xb0080
	v_lshl_add_u64 v[180:181], v[186:187], 0, s[10:11]
	s_addc_u32 s25, s29, 0
	s_add_i32 s28, s59, s37
	global_load_lds_dwordx4 v[180:181], off
	v_lshl_add_u64 v[180:181], s[24:25], 0, v[136:137]
	s_mov_b32 m0, s28
	s_nop 0
	global_load_lds_dwordx4 v[180:181], off
	v_lshl_add_u64 v[180:181], s[24:25], 0, v[138:139]
	s_add_i32 m0, s28, 0x2000
	s_nop 0
	global_load_lds_dwordx4 v[180:181], off
	v_lshl_add_u64 v[180:181], v[226:227], 0, s[10:11]
	s_mov_b32 m0, s42
	s_nop 0
	global_load_lds_dwordx4 v[180:181], off
	v_lshl_add_u64 v[180:181], v[228:229], 0, s[10:11]
	s_mov_b32 m0, s43
	s_nop 0
	global_load_lds_dwordx4 v[180:181], off
	s_waitcnt vmcnt(8)
	s_waitcnt lgkmcnt(0)
	s_barrier
	s_setprio 1
	s_waitcnt lgkmcnt(0)
	v_mfma_f32_16x16x32_bf16 v[60:63], v[128:131], v[194:197], v[60:63]
	v_mfma_f32_16x16x32_bf16 v[56:59], v[148:151], v[194:197], v[56:59]
	v_mfma_f32_16x16x32_bf16 v[52:55], v[128:131], v[202:205], v[52:55]
	v_mfma_f32_16x16x32_bf16 v[48:51], v[148:151], v[202:205], v[48:51]
	v_mfma_f32_16x16x32_bf16 v[40:43], v[128:131], v[210:213], v[40:43]
	v_mfma_f32_16x16x32_bf16 v[32:35], v[148:151], v[210:213], v[32:35]
	v_mfma_f32_16x16x32_bf16 v[24:27], v[128:131], v[218:221], v[24:27]
	v_mfma_f32_16x16x32_bf16 v[16:19], v[148:151], v[218:221], v[16:19]
	v_mfma_f32_16x16x32_bf16 v[60:63], v[132:135], v[198:201], v[60:63]
	v_mfma_f32_16x16x32_bf16 v[56:59], v[160:163], v[198:201], v[56:59]
	v_mfma_f32_16x16x32_bf16 v[52:55], v[132:135], v[206:209], v[52:55]
	v_mfma_f32_16x16x32_bf16 v[48:51], v[160:163], v[206:209], v[48:51]
	v_mfma_f32_16x16x32_bf16 v[40:43], v[132:135], v[214:217], v[40:43]
	v_mfma_f32_16x16x32_bf16 v[32:35], v[160:163], v[214:217], v[32:35]
	v_mfma_f32_16x16x32_bf16 v[24:27], v[132:135], v[222:225], v[24:27]
	v_mfma_f32_16x16x32_bf16 v[16:19], v[160:163], v[222:225], v[16:19]
	s_setprio 0
	s_setprio 1
	v_mfma_f32_16x16x32_bf16 v[44:47], v[164:167], v[194:197], v[44:47]
	v_mfma_f32_16x16x32_bf16 v[36:39], v[172:175], v[194:197], v[36:39]
	v_mfma_f32_16x16x32_bf16 v[28:31], v[164:167], v[202:205], v[28:31]
	v_mfma_f32_16x16x32_bf16 v[20:23], v[172:175], v[202:205], v[20:23]
	v_mfma_f32_16x16x32_bf16 v[12:15], v[164:167], v[210:213], v[12:15]
	v_mfma_f32_16x16x32_bf16 v[8:11], v[172:175], v[210:213], v[8:11]
	v_mfma_f32_16x16x32_bf16 v[4:7], v[164:167], v[218:221], v[4:7]
	v_mfma_f32_16x16x32_bf16 v[0:3], v[172:175], v[218:221], v[0:3]
	v_mfma_f32_16x16x32_bf16 v[44:47], v[168:171], v[198:201], v[44:47]
	v_mfma_f32_16x16x32_bf16 v[36:39], v[176:179], v[198:201], v[36:39]
	v_mfma_f32_16x16x32_bf16 v[28:31], v[168:171], v[206:209], v[28:31]
	v_mfma_f32_16x16x32_bf16 v[20:23], v[176:179], v[206:209], v[20:23]
	v_mfma_f32_16x16x32_bf16 v[12:15], v[168:171], v[214:217], v[12:15]
	v_mfma_f32_16x16x32_bf16 v[8:11], v[176:179], v[214:217], v[8:11]
	v_mfma_f32_16x16x32_bf16 v[4:7], v[168:171], v[222:225], v[4:7]
	v_mfma_f32_16x16x32_bf16 v[0:3], v[176:179], v[222:225], v[0:3]
	s_setprio 0
	s_barrier
	s_add_u32 s55, s55, 0x100
	s_addc_u32 s56, s56, 0
	s_cmp_ge_u32 s57, s53
	s_mov_b64 s[24:25], s[26:27]
	s_mov_b32 s28, s57
	s_cbranch_scc0 .LBB0_1246
	s_mov_b32 s99, 1
	s_and_b64 vcc, exec, s[12:13]
	s_cbranch_vccz .LBB0_1251
	s_barrier
	s_cmp_lt_i32 s2, 0
	s_mov_b64 s[24:25], -1
	s_cbranch_scc1 .LBB0_1252
